# cand30 + sample-row tails of the residual/norm phases: per-chunk gain/bias loads issued up front (fresh registers, copies at the old places, recomputed waits)
# baseline (speedup 1.0000x reference)
.LBB0_779:
	s_cmp_lt_i32 s6, 32
	s_cbranch_scc0 .LBB0_783
	s_ashr_i32 s7, s6, 31
	s_lshl_b64 s[2:3], s[6:7], 12
	s_lshl_b64 s[0:1], s[6:7], 14
	s_add_u32 s16, s8, s0
	s_addc_u32 s15, s9, s1
	s_add_u32 s4, s16, 0x69ac0000
	s_addc_u32 s5, s15, 0
	v_lshlrev_b32_e32 v102, 5, v1
	global_load_dwordx4 v[2:5], v102, s[4:5]
	v_lshlrev_b32_e32 v66, 3, v1
	v_or_b32_e32 v69, 0xe00, v66
	v_lshlrev_b32_e32 v79, 2, v69
	global_load_dwordx4 v[34:37], v79, s[4:5] offset:16
	global_load_dwordx4 v[6:9], v102, s[4:5] offset:16
	global_load_dwordx4 v[14:17], v102, s[4:5] offset:2048
	global_load_dwordx4 v[10:13], v102, s[4:5] offset:2064
	v_or_b32_e32 v103, 0x1000, v102
	global_load_dwordx4 v[22:25], v103, s[4:5]
	global_load_dwordx4 v[18:21], v103, s[4:5] offset:16
	v_or_b32_e32 v104, 0x1800, v102
	global_load_dwordx4 v[30:33], v104, s[4:5]
	global_load_dwordx4 v[26:29], v104, s[4:5] offset:16
	v_or_b32_e32 v72, 0x800, v66
	v_lshlrev_b32_e32 v105, 2, v72
	global_load_dwordx4 v[42:45], v105, s[4:5]
	global_load_dwordx4 v[38:41], v105, s[4:5] offset:16
	v_or_b32_e32 v71, 0xa00, v66
	v_lshlrev_b32_e32 v106, 2, v71
	global_load_dwordx4 v[54:57], v106, s[4:5]
	global_load_dwordx4 v[50:53], v106, s[4:5] offset:16
	v_or_b32_e32 v70, 0xc00, v66
	v_lshlrev_b32_e32 v67, 2, v70
	global_load_dwordx4 v[62:65], v67, s[4:5]
	global_load_dwordx4 v[58:61], v67, s[4:5] offset:16
	global_load_dwordx4 v[46:49], v79, s[4:5]
	s_add_u32 s12, s12, s0
	s_addc_u32 s13, s13, s1
	global_load_dwordx4 v[82:85], v102, s[10:11] offset:16
	global_load_dwordx4 v[86:89], v102, s[10:11]
	global_load_dwordx4 v[90:93], v102, s[12:13] offset:16
	global_load_dwordx4 v[94:97], v102, s[12:13]
	global_load_dwordx4 v[178:181], v102, s[10:11] offset:2048
	global_load_dwordx4 v[182:185], v102, s[12:13] offset:2048
	global_load_dwordx4 v[186:189], v102, s[12:13] offset:2064
	global_load_dwordx4 v[190:193], v102, s[10:11] offset:2064
	global_load_dwordx4 v[194:197], v103, s[10:11]
	global_load_dwordx4 v[198:201], v103, s[12:13]
	global_load_dwordx4 v[202:205], v103, s[12:13] offset:16
	global_load_dwordx4 v[206:209], v103, s[10:11] offset:16
	global_load_dwordx4 v[210:213], v104, s[10:11]
	global_load_dwordx4 v[214:217], v104, s[12:13]
	global_load_dwordx4 v[218:221], v104, s[12:13] offset:16
	global_load_dwordx4 v[222:225], v104, s[10:11] offset:16
	global_load_dwordx4 v[226:229], v105, s[10:11]
	global_load_dwordx4 v[230:233], v105, s[12:13]
	global_load_dwordx4 v[236:239], v105, s[12:13] offset:16
	global_load_dwordx4 v[240:243], v105, s[10:11] offset:16
	global_load_dwordx4 v[244:247], v106, s[10:11]
	global_load_dwordx4 v[248:251], v106, s[12:13]
	v_mbcnt_hi_u32_b32 v68, -1, v234
	v_and_b32_e32 v73, 64, v68
	v_xor_b32_e32 v74, 1, v68
	v_add_u32_e32 v80, 64, v73
	v_cmp_lt_i32_e32 vcc, v74, v80
	s_mov_b32 s14, 0xf800000
	s_add_u32 s4, s16, 0x69b40000
	v_cndmask_b32_e32 v73, v68, v74, vcc
	v_lshlrev_b32_e32 v73, 2, v73
	s_addc_u32 s5, s15, 0
	v_lshlrev_b32_e32 v72, 1, v72
	v_lshlrev_b32_e32 v71, 1, v71
	v_lshlrev_b32_e32 v70, 1, v70
	s_waitcnt vmcnt(37)
	v_mul_f32_e32 v76, v3, v3
	v_fmac_f32_e32 v76, v2, v2
	v_fmac_f32_e32 v76, v4, v4
	v_fmac_f32_e32 v76, v5, v5
	s_waitcnt vmcnt(35)
	v_fmac_f32_e32 v76, v6, v6
	v_fmac_f32_e32 v76, v7, v7
	v_fmac_f32_e32 v76, v8, v8
	v_fmac_f32_e32 v76, v9, v9
	s_waitcnt vmcnt(34)
	v_fmac_f32_e32 v76, v14, v14
	v_fmac_f32_e32 v76, v15, v15
	v_fmac_f32_e32 v76, v16, v16
	v_fmac_f32_e32 v76, v17, v17
	s_waitcnt vmcnt(33)
	v_fmac_f32_e32 v76, v10, v10
	v_fmac_f32_e32 v76, v11, v11
	v_fmac_f32_e32 v76, v12, v12
	v_fmac_f32_e32 v76, v13, v13
	s_waitcnt vmcnt(32)
	v_fmac_f32_e32 v76, v22, v22
	v_fmac_f32_e32 v76, v23, v23
	v_fmac_f32_e32 v76, v24, v24
	v_fmac_f32_e32 v76, v25, v25
	s_waitcnt vmcnt(31)
	v_fmac_f32_e32 v76, v18, v18
	v_fmac_f32_e32 v76, v19, v19
	v_fmac_f32_e32 v76, v20, v20
	v_fmac_f32_e32 v76, v21, v21
	s_waitcnt vmcnt(30)
	v_fmac_f32_e32 v76, v30, v30
	v_fmac_f32_e32 v76, v31, v31
	v_fmac_f32_e32 v76, v32, v32
	v_fmac_f32_e32 v76, v33, v33
	s_waitcnt vmcnt(29)
	v_fmac_f32_e32 v76, v26, v26
	v_fmac_f32_e32 v76, v27, v27
	v_fmac_f32_e32 v76, v28, v28
	v_fmac_f32_e32 v76, v29, v29
	s_waitcnt vmcnt(28)
	v_fmac_f32_e32 v76, v42, v42
	v_fmac_f32_e32 v76, v43, v43
	v_fmac_f32_e32 v76, v44, v44
	v_fmac_f32_e32 v76, v45, v45
	s_waitcnt vmcnt(27)
	v_fmac_f32_e32 v76, v38, v38
	v_fmac_f32_e32 v76, v39, v39
	v_fmac_f32_e32 v76, v40, v40
	v_fmac_f32_e32 v76, v41, v41
	s_waitcnt vmcnt(26)
	v_fmac_f32_e32 v76, v54, v54
	v_fmac_f32_e32 v76, v55, v55
	v_fmac_f32_e32 v76, v56, v56
	v_fmac_f32_e32 v76, v57, v57
	s_waitcnt vmcnt(25)
	v_fmac_f32_e32 v76, v50, v50
	v_fmac_f32_e32 v76, v51, v51
	v_fmac_f32_e32 v76, v52, v52
	v_fmac_f32_e32 v76, v53, v53
	s_waitcnt vmcnt(24)
	v_fmac_f32_e32 v76, v62, v62
	v_fmac_f32_e32 v76, v63, v63
	v_fmac_f32_e32 v76, v64, v64
	v_fmac_f32_e32 v76, v65, v65
	s_waitcnt vmcnt(23)
	v_fmac_f32_e32 v76, v58, v58
	v_fmac_f32_e32 v76, v59, v59
	v_fmac_f32_e32 v76, v60, v60
	v_fmac_f32_e32 v76, v61, v61
	s_waitcnt vmcnt(22)
	v_fmac_f32_e32 v76, v46, v46
	v_fmac_f32_e32 v76, v47, v47
	v_fmac_f32_e32 v76, v48, v48
	v_fmac_f32_e32 v76, v49, v49
	v_fmac_f32_e32 v76, v34, v34
	v_pk_mul_f32 v[74:75], v[36:37], v[36:37]
	v_fmac_f32_e32 v76, v35, v35
	v_add_f32_e32 v74, v74, v76
	v_add_f32_e32 v74, v75, v74
	v_xor_b32_e32 v76, 2, v68
	v_cmp_lt_i32_e32 vcc, v76, v80
	s_waitcnt lgkmcnt(0)
	s_nop 1
	v_add_f32_dpp v74, v74, v74 quad_perm:[1,0,3,2] row_mask:0xf bank_mask:0xf
	v_cndmask_b32_e32 v76, v68, v76, vcc
	v_lshlrev_b32_e32 v78, 2, v76
	v_xor_b32_e32 v76, 4, v68
	v_cmp_lt_i32_e32 vcc, v76, v80
	s_waitcnt lgkmcnt(0)
	s_nop 1
	v_add_f32_dpp v74, v74, v74 quad_perm:[2,3,0,1] row_mask:0xf bank_mask:0xf
	v_cndmask_b32_e32 v76, v68, v76, vcc
	v_lshlrev_b32_e32 v77, 2, v76
	v_xor_b32_e32 v76, 8, v68
	v_cmp_lt_i32_e32 vcc, v76, v80
	s_waitcnt lgkmcnt(0)
	s_nop 1
	v_add_f32_dpp v74, v74, v74 row_half_mirror row_mask:0xf bank_mask:0xf
	v_cndmask_b32_e32 v76, v68, v76, vcc
	v_lshlrev_b32_e32 v76, 2, v76
	v_xor_b32_e32 v75, 16, v68
	v_cmp_lt_i32_e32 vcc, v75, v80
	s_waitcnt lgkmcnt(0)
	s_nop 1
	v_add_f32_dpp v81, v74, v74 row_mirror row_mask:0xf bank_mask:0xf
	v_cndmask_b32_e32 v75, v68, v75, vcc
	v_lshlrev_b32_e32 v75, 2, v75
	v_xor_b32_e32 v74, 32, v68
	v_cmp_lt_i32_e32 vcc, v74, v80
	s_nop 1
	v_cndmask_b32_e32 v68, v68, v74, vcc
	v_lshlrev_b32_e32 v74, 2, v68
	s_waitcnt lgkmcnt(0)
	v_mov_b32_e32 v68, v81
	v_mov_b32_e32 v98, v81
	s_nop 1
	v_permlane16_swap_b32_e32 v98, v68
	v_add_f32_e32 v68, v68, v98
	v_mov_b32_e32 v81, 0x358637bd
	s_waitcnt lgkmcnt(0)
	v_mov_b32_e32 v80, v68
	s_nop 1
	v_permlane32_swap_b32_e32 v80, v68
	v_add_f32_e32 v68, v68, v80
	v_fmamk_f32 v68, v68, 0x39800000, v81
	v_mul_f32_e32 v80, 0x4f800000, v68
	v_cmp_gt_f32_e32 vcc, s14, v68
	s_nop 1
	v_cndmask_b32_e32 v68, v68, v80, vcc
	v_sqrt_f32_e32 v98, v68
	v_mov_b32_e32 v80, 0x260
	v_add_u32_e32 v99, -1, v98
	v_add_u32_e32 v100, 1, v98
	v_fma_f32 v101, -v99, v98, v68
	v_fma_f32 v107, -v100, v98, v68
	v_cmp_ge_f32_e64 s[0:1], 0, v101
	s_nop 1
	v_cndmask_b32_e64 v98, v98, v99, s[0:1]
	v_cmp_lt_f32_e64 s[0:1], 0, v107
	s_nop 1
	v_cndmask_b32_e64 v98, v98, v100, s[0:1]
	v_mul_f32_e32 v99, 0x37800000, v98
	v_cndmask_b32_e32 v98, v98, v99, vcc
	v_cmp_class_f32_e32 vcc, v68, v80
	s_nop 1
	v_cndmask_b32_e32 v68, v98, v68, vcc
	v_div_scale_f32 v98, s[0:1], v68, v68, 1.0
	v_rcp_f32_e32 v99, v98
	v_div_scale_f32 v100, vcc, 1.0, v68, 1.0
	s_lshl_b64 s[0:1], s[6:7], 13
	v_fma_f32 v101, -v98, v99, 1.0
	v_fmac_f32_e32 v99, v101, v99
	v_mul_f32_e32 v101, v100, v99
	v_fma_f32 v107, -v98, v101, v100
	v_fmac_f32_e32 v101, v107, v99
	v_fma_f32 v98, -v98, v101, v100
	v_div_fmas_f32 v98, v98, v99, v101
	v_div_fixup_f32 v68, v98, v68, 1.0
	v_pk_mul_f32 v[2:3], v[2:3], v[68:69] op_sel_hi:[1,0]
	v_pk_mul_f32 v[4:5], v[4:5], v[68:69] op_sel_hi:[1,0]
	v_pk_mul_f32 v[98:99], v[6:7], v[68:69] op_sel_hi:[1,0]
	v_pk_mul_f32 v[100:101], v[8:9], v[68:69] op_sel_hi:[1,0]
	s_waitcnt vmcnt(18)
	v_pk_fma_f32 v[6:7], v[86:87], v[2:3], v[94:95]
	v_pk_fma_f32 v[8:9], v[88:89], v[4:5], v[96:97]
	v_pk_fma_f32 v[2:3], v[82:83], v[98:99], v[90:91]
	v_pk_fma_f32 v[4:5], v[84:85], v[100:101], v[92:93]
	global_store_dwordx4 v102, v[6:9], s[4:5]
	global_store_dwordx4 v102, v[2:5], s[4:5] offset:16
	s_nop 1
	s_waitcnt vmcnt(19)
	v_mov_b64_e32 v[82:83], v[178:179]
	v_mov_b64_e32 v[84:85], v[180:181]
	s_waitcnt vmcnt(18)
	v_mov_b64_e32 v[86:87], v[182:183]
	v_mov_b64_e32 v[88:89], v[184:185]
	s_waitcnt vmcnt(17)
	v_mov_b64_e32 v[90:91], v[186:187]
	v_mov_b64_e32 v[92:93], v[188:189]
	s_waitcnt vmcnt(16)
	v_mov_b64_e32 v[94:95], v[190:191]
	v_mov_b64_e32 v[96:97], v[192:193]
	v_pk_mul_f32 v[14:15], v[14:15], v[68:69] op_sel_hi:[1,0]
	v_pk_mul_f32 v[16:17], v[16:17], v[68:69] op_sel_hi:[1,0]
	v_pk_mul_f32 v[10:11], v[10:11], v[68:69] op_sel_hi:[1,0]
	v_pk_mul_f32 v[12:13], v[12:13], v[68:69] op_sel_hi:[1,0]
	v_pk_mul_f32 v[22:23], v[22:23], v[68:69] op_sel_hi:[1,0]
	v_pk_mul_f32 v[24:25], v[24:25], v[68:69] op_sel_hi:[1,0]
	v_pk_mul_f32 v[18:19], v[18:19], v[68:69] op_sel_hi:[1,0]
	v_pk_mul_f32 v[20:21], v[20:21], v[68:69] op_sel_hi:[1,0]
	v_pk_mul_f32 v[30:31], v[30:31], v[68:69] op_sel_hi:[1,0]
	v_pk_mul_f32 v[32:33], v[32:33], v[68:69] op_sel_hi:[1,0]
	v_pk_mul_f32 v[26:27], v[26:27], v[68:69] op_sel_hi:[1,0]
	v_pk_mul_f32 v[28:29], v[28:29], v[68:69] op_sel_hi:[1,0]
	v_pk_mul_f32 v[42:43], v[42:43], v[68:69] op_sel_hi:[1,0]
	v_pk_mul_f32 v[44:45], v[44:45], v[68:69] op_sel_hi:[1,0]
	v_pk_mul_f32 v[38:39], v[38:39], v[68:69] op_sel_hi:[1,0]
	v_pk_mul_f32 v[40:41], v[40:41], v[68:69] op_sel_hi:[1,0]
	v_pk_mul_f32 v[54:55], v[54:55], v[68:69] op_sel_hi:[1,0]
	v_pk_mul_f32 v[56:57], v[56:57], v[68:69] op_sel_hi:[1,0]
	v_pk_mul_f32 v[50:51], v[50:51], v[68:69] op_sel_hi:[1,0]
	v_pk_mul_f32 v[52:53], v[52:53], v[68:69] op_sel_hi:[1,0]
	v_pk_mul_f32 v[62:63], v[62:63], v[68:69] op_sel_hi:[1,0]
	v_pk_mul_f32 v[64:65], v[64:65], v[68:69] op_sel_hi:[1,0]
	v_pk_mul_f32 v[58:59], v[58:59], v[68:69] op_sel_hi:[1,0]
	v_pk_mul_f32 v[60:61], v[60:61], v[68:69] op_sel_hi:[1,0]
	v_pk_mul_f32 v[98:99], v[46:47], v[68:69] op_sel_hi:[1,0]
	v_pk_mul_f32 v[100:101], v[48:49], v[68:69] op_sel_hi:[1,0]
	v_pk_mul_f32 v[108:109], v[8:9], v[8:9]
	v_pk_mul_f32 v[110:111], v[2:3], v[2:3]
	v_pk_mul_f32 v[112:113], v[4:5], v[4:5]
	s_add_u32 s0, s8, s0
	s_addc_u32 s1, s9, s1
	s_add_u32 s8, s0, 0x69900000
	s_addc_u32 s9, s1, 0
	v_pk_fma_f32 v[14:15], v[82:83], v[14:15], v[86:87]
	v_pk_fma_f32 v[16:17], v[84:85], v[16:17], v[88:89]
	v_pk_fma_f32 v[10:11], v[94:95], v[10:11], v[90:91]
	v_pk_fma_f32 v[12:13], v[96:97], v[12:13], v[92:93]
	global_store_dwordx4 v102, v[14:17], s[4:5] offset:2048
	global_store_dwordx4 v102, v[10:13], s[4:5] offset:2064
	s_nop 1
	s_waitcnt vmcnt(17)
	v_mov_b64_e32 v[82:83], v[194:195]
	v_mov_b64_e32 v[84:85], v[196:197]
	s_waitcnt vmcnt(16)
	v_mov_b64_e32 v[86:87], v[198:199]
	v_mov_b64_e32 v[88:89], v[200:201]
	s_waitcnt vmcnt(15)
	v_mov_b64_e32 v[90:91], v[202:203]
	v_mov_b64_e32 v[92:93], v[204:205]
	s_waitcnt vmcnt(14)
	v_mov_b64_e32 v[94:95], v[206:207]
	v_mov_b64_e32 v[96:97], v[208:209]
	v_pk_fma_f32 v[22:23], v[82:83], v[22:23], v[86:87]
	v_pk_fma_f32 v[24:25], v[84:85], v[24:25], v[88:89]
	v_pk_fma_f32 v[18:19], v[94:95], v[18:19], v[90:91]
	v_pk_fma_f32 v[20:21], v[96:97], v[20:21], v[92:93]
	global_store_dwordx4 v103, v[22:25], s[4:5]
	global_store_dwordx4 v103, v[18:21], s[4:5] offset:16
	s_nop 1
	s_waitcnt vmcnt(15)
	v_mov_b64_e32 v[82:83], v[210:211]
	v_mov_b64_e32 v[84:85], v[212:213]
	s_waitcnt vmcnt(14)
	v_mov_b64_e32 v[86:87], v[214:215]
	v_mov_b64_e32 v[88:89], v[216:217]
	s_waitcnt vmcnt(13)
	v_mov_b64_e32 v[90:91], v[218:219]
	v_mov_b64_e32 v[92:93], v[220:221]
	s_waitcnt vmcnt(12)
	v_mov_b64_e32 v[94:95], v[222:223]
	v_mov_b64_e32 v[96:97], v[224:225]
	v_pk_mul_f32 v[102:103], v[34:35], v[68:69] op_sel_hi:[1,0]
	v_pk_fma_f32 v[30:31], v[82:83], v[30:31], v[86:87]
	v_pk_fma_f32 v[32:33], v[84:85], v[32:33], v[88:89]
	v_pk_fma_f32 v[26:27], v[94:95], v[26:27], v[90:91]
	v_pk_fma_f32 v[28:29], v[96:97], v[28:29], v[92:93]
	global_store_dwordx4 v104, v[30:33], s[4:5]
	global_store_dwordx4 v104, v[26:29], s[4:5] offset:16
	s_nop 1
	s_waitcnt vmcnt(13)
	v_mov_b64_e32 v[82:83], v[226:227]
	v_mov_b64_e32 v[84:85], v[228:229]
	s_waitcnt vmcnt(12)
	v_mov_b64_e32 v[86:87], v[230:231]
	v_mov_b64_e32 v[88:89], v[232:233]
	s_waitcnt vmcnt(11)
	v_mov_b64_e32 v[90:91], v[236:237]
	v_mov_b64_e32 v[92:93], v[238:239]
	s_waitcnt vmcnt(10)
	v_mov_b64_e32 v[94:95], v[240:241]
	v_mov_b64_e32 v[96:97], v[242:243]
	v_pk_fma_f32 v[42:43], v[82:83], v[42:43], v[86:87]
	v_pk_fma_f32 v[44:45], v[84:85], v[44:45], v[88:89]
	v_pk_fma_f32 v[38:39], v[94:95], v[38:39], v[90:91]
	v_pk_fma_f32 v[40:41], v[96:97], v[40:41], v[92:93]
	global_store_dwordx4 v105, v[42:45], s[4:5]
	global_store_dwordx4 v105, v[38:41], s[4:5] offset:16
	s_nop 1
	s_waitcnt vmcnt(11)
	v_mov_b64_e32 v[82:83], v[244:245]
	v_mov_b64_e32 v[84:85], v[246:247]
	s_waitcnt vmcnt(10)
	v_mov_b64_e32 v[86:87], v[248:249]
	v_mov_b64_e32 v[88:89], v[250:251]
	global_load_dwordx4 v[90:93], v106, s[12:13] offset:16
	global_load_dwordx4 v[94:97], v106, s[10:11] offset:16
	v_pk_mul_f32 v[104:105], v[36:37], v[68:69] op_sel_hi:[1,0]
	v_pk_fma_f32 v[54:55], v[82:83], v[54:55], v[86:87]
	v_pk_fma_f32 v[56:57], v[84:85], v[56:57], v[88:89]
	s_waitcnt vmcnt(0)
	v_pk_fma_f32 v[50:51], v[94:95], v[50:51], v[90:91]
	v_pk_fma_f32 v[52:53], v[96:97], v[52:53], v[92:93]
	global_store_dwordx4 v106, v[54:57], s[4:5]
	global_store_dwordx4 v106, v[50:53], s[4:5] offset:16
	global_load_dwordx4 v[82:85], v67, s[10:11]
	global_load_dwordx4 v[86:89], v67, s[12:13]
	global_load_dwordx4 v[90:93], v67, s[12:13] offset:16
	global_load_dwordx4 v[94:97], v67, s[10:11] offset:16
	v_pk_mul_f32 v[106:107], v[6:7], v[6:7]
	s_waitcnt vmcnt(2)
	v_pk_fma_f32 v[46:47], v[82:83], v[62:63], v[86:87]
	v_pk_fma_f32 v[48:49], v[84:85], v[64:65], v[88:89]
	s_waitcnt vmcnt(0)
	v_pk_fma_f32 v[34:35], v[94:95], v[58:59], v[90:91]
	v_pk_fma_f32 v[36:37], v[96:97], v[60:61], v[92:93]
	global_store_dwordx4 v67, v[46:49], s[4:5]
	global_store_dwordx4 v67, v[34:37], s[4:5] offset:16
	global_load_dwordx4 v[58:61], v79, s[12:13] offset:16
	global_load_dwordx4 v[62:65], v79, s[12:13]
	global_load_dwordx4 v[82:85], v79, s[10:11] offset:16
	global_load_dwordx4 v[86:89], v79, s[10:11]
	v_add_f32_e32 v67, v106, v107
	v_add_f32_e32 v67, v108, v67
	v_add_f32_e32 v67, v109, v67
	v_add_f32_e32 v67, v110, v67
	v_add_f32_e32 v67, v111, v67
	v_add_f32_e32 v67, v112, v67
	v_add_f32_e32 v67, v113, v67
	v_pk_mul_f32 v[90:91], v[14:15], v[14:15]
	v_pk_mul_f32 v[92:93], v[16:17], v[16:17]
	v_add_f32_e32 v67, v90, v67
	v_add_f32_e32 v67, v91, v67
	v_add_f32_e32 v67, v92, v67
	v_pk_mul_f32 v[94:95], v[10:11], v[10:11]
	v_add_f32_e32 v67, v93, v67
	v_add_f32_e32 v67, v94, v67
	v_pk_mul_f32 v[96:97], v[12:13], v[12:13]
	v_add_f32_e32 v67, v95, v67
	v_add_f32_e32 v67, v96, v67
	v_add_f32_e32 v67, v97, v67
	v_pk_mul_f32 v[90:91], v[22:23], v[22:23]
	v_pk_mul_f32 v[92:93], v[24:25], v[24:25]
	v_add_f32_e32 v67, v90, v67
	v_add_f32_e32 v67, v91, v67
	v_add_f32_e32 v67, v92, v67
	v_pk_mul_f32 v[94:95], v[18:19], v[18:19]
	v_add_f32_e32 v67, v93, v67
	v_add_f32_e32 v67, v94, v67
	v_pk_mul_f32 v[96:97], v[20:21], v[20:21]
	v_add_f32_e32 v67, v95, v67
	v_add_f32_e32 v67, v96, v67
	v_add_f32_e32 v67, v97, v67
	v_pk_mul_f32 v[90:91], v[30:31], v[30:31]
	v_pk_mul_f32 v[92:93], v[32:33], v[32:33]
	v_add_f32_e32 v67, v90, v67
	v_add_f32_e32 v67, v91, v67
	v_add_f32_e32 v67, v92, v67
	v_pk_mul_f32 v[94:95], v[26:27], v[26:27]
	v_add_f32_e32 v67, v93, v67
	v_add_f32_e32 v67, v94, v67
	v_pk_mul_f32 v[96:97], v[28:29], v[28:29]
	v_add_f32_e32 v67, v95, v67
	v_add_f32_e32 v67, v96, v67
	v_add_f32_e32 v67, v97, v67
	v_pk_mul_f32 v[90:91], v[42:43], v[42:43]
	v_pk_mul_f32 v[92:93], v[44:45], v[44:45]
	v_add_f32_e32 v67, v90, v67
	v_add_f32_e32 v67, v91, v67
	v_add_f32_e32 v67, v92, v67
	v_pk_mul_f32 v[94:95], v[38:39], v[38:39]
	v_add_f32_e32 v67, v93, v67
	v_add_f32_e32 v67, v94, v67
	v_pk_mul_f32 v[96:97], v[40:41], v[40:41]
	v_add_f32_e32 v67, v95, v67
	v_add_f32_e32 v67, v96, v67
	v_add_f32_e32 v67, v97, v67
	v_pk_mul_f32 v[90:91], v[54:55], v[54:55]
	v_pk_mul_f32 v[92:93], v[56:57], v[56:57]
	v_add_f32_e32 v67, v90, v67
	v_add_f32_e32 v67, v91, v67
	v_add_f32_e32 v67, v92, v67
	v_pk_mul_f32 v[94:95], v[50:51], v[50:51]
	v_add_f32_e32 v67, v93, v67
	v_add_f32_e32 v67, v94, v67
	v_pk_mul_f32 v[96:97], v[52:53], v[52:53]
	v_add_f32_e32 v67, v95, v67
	v_add_f32_e32 v67, v96, v67
	v_add_f32_e32 v67, v97, v67
	v_pk_mul_f32 v[90:91], v[46:47], v[46:47]
	v_pk_mul_f32 v[92:93], v[48:49], v[48:49]
	v_add_f32_e32 v67, v90, v67
	v_add_f32_e32 v67, v91, v67
	v_add_f32_e32 v67, v92, v67
	v_pk_mul_f32 v[94:95], v[34:35], v[34:35]
	v_add_f32_e32 v67, v93, v67
	v_add_f32_e32 v67, v94, v67
	v_pk_mul_f32 v[96:97], v[36:37], v[36:37]
	v_add_f32_e32 v67, v95, v67
	v_add_f32_e32 v67, v96, v67
	v_add_f32_e32 v67, v97, v67
	s_waitcnt vmcnt(0)
	v_pk_fma_f32 v[62:63], v[86:87], v[98:99], v[62:63]
	v_pk_fma_f32 v[58:59], v[82:83], v[102:103], v[58:59]
	v_pk_mul_f32 v[82:83], v[62:63], v[62:63]
	v_pk_fma_f32 v[64:65], v[88:89], v[100:101], v[64:65]
	v_add_f32_e32 v67, v82, v67
	v_pk_fma_f32 v[60:61], v[84:85], v[104:105], v[60:61]
	v_pk_mul_f32 v[84:85], v[64:65], v[64:65]
	v_add_f32_e32 v67, v83, v67
	v_add_f32_e32 v67, v84, v67
	v_pk_mul_f32 v[86:87], v[58:59], v[58:59]
	v_add_f32_e32 v67, v85, v67
	v_add_f32_e32 v67, v86, v67
	v_pk_mul_f32 v[88:89], v[60:61], v[60:61]
	v_add_f32_e32 v67, v87, v67
	v_add_f32_e32 v67, v88, v67
	v_add_f32_e32 v67, v89, v67
	global_store_dwordx4 v79, v[62:65], s[4:5]
	global_store_dwordx4 v79, v[58:61], s[4:5] offset:16
	s_movk_i32 s10, 0x7fff
	s_waitcnt lgkmcnt(0)
	s_nop 1
	v_add_f32_dpp v67, v67, v67 quad_perm:[1,0,3,2] row_mask:0xf bank_mask:0xf
	s_waitcnt lgkmcnt(0)
	s_nop 1
	v_add_f32_dpp v67, v67, v67 quad_perm:[2,3,0,1] row_mask:0xf bank_mask:0xf
	s_waitcnt lgkmcnt(0)
	s_nop 1
	v_add_f32_dpp v67, v67, v67 row_half_mirror row_mask:0xf bank_mask:0xf
	s_waitcnt lgkmcnt(0)
	s_nop 1
	v_add_f32_dpp v68, v67, v67 row_mirror row_mask:0xf bank_mask:0xf
	v_mov_b32_e32 v67, 0
	s_waitcnt lgkmcnt(0)
	v_mov_b32_e32 v82, v68
	s_nop 1
	v_permlane16_swap_b32_e32 v82, v68
	v_add_f32_e32 v68, v68, v82
	s_waitcnt lgkmcnt(0)
	v_mov_b32_e32 v82, v68
	s_nop 1
	v_permlane32_swap_b32_e32 v82, v68
	v_add_f32_e32 v68, v68, v82
	v_fmac_f32_e32 v81, 0x39800000, v68
	v_mul_f32_e32 v68, 0x4f800000, v81
	v_cmp_gt_f32_e32 vcc, s14, v81
	s_nop 1
	v_cndmask_b32_e32 v68, v81, v68, vcc
	v_sqrt_f32_e32 v81, v68
	s_nop 0
	v_add_u32_e32 v82, -1, v81
	v_add_u32_e32 v83, 1, v81
	v_fma_f32 v84, -v82, v81, v68
	v_fma_f32 v85, -v83, v81, v68
	v_cmp_ge_f32_e64 s[0:1], 0, v84
	s_nop 1
	v_cndmask_b32_e64 v81, v81, v82, s[0:1]
	v_cmp_lt_f32_e64 s[0:1], 0, v85
	s_nop 1
	v_cndmask_b32_e64 v81, v81, v83, s[0:1]
	v_mul_f32_e32 v82, 0x37800000, v81
	v_cndmask_b32_e32 v81, v81, v82, vcc
	v_cmp_class_f32_e32 vcc, v68, v80
	s_nop 1
	v_cndmask_b32_e32 v68, v81, v68, vcc
	v_div_scale_f32 v80, s[0:1], v68, v68, 1.0
	v_rcp_f32_e32 v81, v80
	v_div_scale_f32 v79, vcc, 1.0, v68, 1.0
	v_fma_f32 v82, -v80, v81, 1.0
	v_fmac_f32_e32 v81, v82, v81
	v_mul_f32_e32 v82, v79, v81
	v_fma_f32 v83, -v80, v82, v79
	v_fmac_f32_e32 v82, v83, v81
	v_fma_f32 v79, -v80, v82, v79
	v_div_fmas_f32 v79, v79, v81, v82
	v_div_fixup_f32 v68, v79, v68, 1.0
	v_mul_f32_e32 v6, v6, v68
	v_mul_f32_e32 v7, v7, v68
	v_mul_f32_e32 v8, v8, v68
	v_mul_f32_e32 v9, v9, v68
	v_mul_f32_e32 v17, v17, v68
	v_mul_f32_e32 v21, v21, v68
	v_mul_f32_e32 v88, v26, v68
	v_mul_f32_e32 v89, v27, v68
	v_mul_f32_e32 v96, v38, v68
	v_mul_f32_e32 v97, v39, v68
	v_bfe_u32 v26, v6, 16, 1
	v_bfe_u32 v27, v7, 16, 1
	v_mul_f32_e32 v79, v2, v68
	v_mul_f32_e32 v80, v3, v68
	v_mul_f32_e32 v82, v5, v68
	v_mul_f32_e32 v25, v25, v68
	v_mul_f32_e32 v90, v28, v68
	v_mul_f32_e32 v91, v29, v68
	v_mul_f32_e32 v98, v40, v68
	v_mul_f32_e32 v99, v41, v68
	v_mul_f32_e32 v111, v49, v68
	v_mul_f32_e32 v115, v37, v68
	v_mul_f32_e32 v116, v62, v68
	v_mul_f32_e32 v117, v63, v68
	v_cvt_pk_bf16_f32 v2, v6, v7
	v_cvt_pk_bf16_f32 v3, v8, v9
	v_bfe_u32 v28, v8, 16, 1
	v_bfe_u32 v29, v9, 16, 1
	v_bfe_u32 v37, v17, 16, 1
	v_bfe_u32 v49, v21, 16, 1
	v_bfe_u32 v62, v96, 16, 1
	v_bfe_u32 v63, v97, 16, 1
	v_add3_u32 v6, v6, v26, s10
	v_add3_u32 v7, v7, v27, s10
	v_mul_f32_e32 v81, v4, v68
	v_mul_f32_e32 v14, v14, v68
	v_mul_f32_e32 v15, v15, v68
	v_mul_f32_e32 v16, v16, v68
	v_mul_f32_e32 v84, v30, v68
	v_mul_f32_e32 v85, v31, v68
	v_mul_f32_e32 v87, v33, v68
	v_mul_f32_e32 v92, v42, v68
	v_mul_f32_e32 v93, v43, v68
	v_mul_f32_e32 v95, v45, v68
	v_mul_f32_e32 v118, v64, v68
	v_mul_f32_e32 v119, v65, v68
	v_cvt_pk_bf16_f32 v4, v79, v80
	v_cvt_pk_bf16_f32 v5, v81, v82
	v_bfe_u32 v30, v79, 16, 1
	v_bfe_u32 v31, v80, 16, 1
	v_bfe_u32 v33, v82, 16, 1
	v_bfe_u32 v45, v25, 16, 1
	v_bfe_u32 v64, v98, 16, 1
	v_bfe_u32 v65, v99, 16, 1
	global_store_dwordx4 v130, v[2:5], s[8:9]
	v_add3_u32 v8, v8, v28, s10
	v_add3_u32 v9, v9, v29, s10
	v_cvt_pk_bf16_f32 v2, v14, v15
	v_cvt_pk_bf16_f32 v3, v16, v17
	v_add3_u32 v17, v17, v37, s10
	v_add3_u32 v37, v21, v49, s10
	v_add3_u32 v154, v96, v62, s10
	v_add3_u32 v155, v97, v63, s10
	v_and_b32_e32 v62, 0xffff0000, v6
	v_and_b32_e32 v63, 0xffff0000, v7
	v_mul_f32_e32 v86, v32, v68
	v_mul_f32_e32 v94, v44, v68
	v_mul_f32_e32 v120, v58, v68
	v_mul_f32_e32 v121, v59, v68
	v_bfe_u32 v32, v81, 16, 1
	v_bfe_u32 v58, v92, 16, 1
	v_bfe_u32 v59, v93, 16, 1
	v_add3_u32 v26, v79, v30, s10
	v_add3_u32 v27, v80, v31, s10
	v_add3_u32 v29, v82, v33, s10
	v_add3_u32 v33, v25, v45, s10
	v_add3_u32 v156, v98, v64, s10
	v_add3_u32 v157, v99, v65, s10
	v_and_b32_e32 v64, 0xffff0000, v8
	v_and_b32_e32 v65, 0xffff0000, v9
	v_and_b32_e32 v45, 0xffff0000, v37
	v_max3_f32 v37, |v62|, 0, |v63|
	v_mul_f32_e32 v10, v10, v68
	v_mul_f32_e32 v11, v11, v68
	v_mul_f32_e32 v12, v12, v68
	v_mul_f32_e32 v13, v13, v68
	v_mul_f32_e32 v22, v22, v68
	v_mul_f32_e32 v23, v23, v68
	v_mul_f32_e32 v24, v24, v68
	v_mul_f32_e32 v18, v18, v68
	v_mul_f32_e32 v19, v19, v68
	v_mul_f32_e32 v20, v20, v68
	v_mul_f32_e32 v100, v54, v68
	v_mul_f32_e32 v101, v55, v68
	v_mul_f32_e32 v102, v56, v68
	v_mul_f32_e32 v103, v57, v68
	v_mul_f32_e32 v104, v50, v68
	v_mul_f32_e32 v105, v51, v68
	v_mul_f32_e32 v106, v52, v68
	v_mul_f32_e32 v107, v53, v68
	v_mul_f32_e32 v108, v46, v68
	v_mul_f32_e32 v109, v47, v68
	v_mul_f32_e32 v110, v48, v68
	v_mul_f32_e32 v112, v34, v68
	v_mul_f32_e32 v113, v35, v68
	v_mul_f32_e32 v114, v36, v68
	v_mul_f32_e32 v122, v60, v68
	v_mul_f32_e32 v68, v61, v68
	v_bfe_u32 v34, v14, 16, 1
	v_bfe_u32 v35, v15, 16, 1
	v_bfe_u32 v60, v94, 16, 1
	v_bfe_u32 v61, v95, 16, 1
	v_add3_u32 v28, v81, v32, s10
	v_add3_u32 v150, v92, v58, s10
	v_add3_u32 v151, v93, v59, s10
	v_and_b32_e32 v58, 0xffff0000, v26
	v_and_b32_e32 v59, 0xffff0000, v27
	v_max3_f32 v37, v37, |v64|, |v65|
	v_bfe_u32 v36, v16, 16, 1
	v_bfe_u32 v54, v88, 16, 1
	v_bfe_u32 v55, v89, 16, 1
	v_add3_u32 v14, v14, v34, s10
	v_add3_u32 v15, v15, v35, s10
	v_add3_u32 v152, v94, v60, s10
	v_add3_u32 v153, v95, v61, s10
	v_and_b32_e32 v60, 0xffff0000, v28
	v_and_b32_e32 v61, 0xffff0000, v29
	v_max3_f32 v37, v37, |v58|, |v59|
	v_bfe_u32 v38, v10, 16, 1
	v_bfe_u32 v39, v11, 16, 1
	v_bfe_u32 v56, v90, 16, 1
	v_bfe_u32 v57, v91, 16, 1
	v_add3_u32 v16, v16, v36, s10
	v_add3_u32 v79, v88, v54, s10
	v_add3_u32 v147, v89, v55, s10
	v_and_b32_e32 v54, 0xffff0000, v14
	v_and_b32_e32 v55, 0xffff0000, v15
	v_max3_f32 v37, v37, |v60|, |v61|
	v_bfe_u32 v40, v12, 16, 1
	v_bfe_u32 v41, v13, 16, 1
	v_bfe_u32 v50, v84, 16, 1
	v_bfe_u32 v51, v85, 16, 1
	v_cvt_pk_bf16_f32 v4, v10, v11
	v_add3_u32 v10, v10, v38, s10
	v_add3_u32 v11, v11, v39, s10
	v_add3_u32 v148, v90, v56, s10
	v_add3_u32 v149, v91, v57, s10
	v_and_b32_e32 v56, 0xffff0000, v16
	v_and_b32_e32 v57, 0xffff0000, v17
	v_max3_f32 v37, v37, |v54|, |v55|
	v_bfe_u32 v42, v22, 16, 1
	v_bfe_u32 v43, v23, 16, 1
	v_bfe_u32 v52, v86, 16, 1
	v_bfe_u32 v53, v87, 16, 1
	v_cvt_pk_bf16_f32 v5, v12, v13
	v_add3_u32 v12, v12, v40, s10
	v_add3_u32 v13, v13, v41, s10
	v_add3_u32 v38, v84, v50, s10
	v_add3_u32 v39, v85, v51, s10
	v_and_b32_e32 v50, 0xffff0000, v10
	v_and_b32_e32 v51, 0xffff0000, v11
	v_max3_f32 v37, v37, |v56|, |v57|
	v_bfe_u32 v44, v24, 16, 1
	v_bfe_u32 v46, v18, 16, 1
	v_bfe_u32 v47, v19, 16, 1
	v_add3_u32 v30, v22, v42, s10
	v_add3_u32 v31, v23, v43, s10
	v_add3_u32 v40, v86, v52, s10
	v_add3_u32 v41, v87, v53, s10
	v_and_b32_e32 v52, 0xffff0000, v12
	v_and_b32_e32 v53, 0xffff0000, v13
	v_max3_f32 v37, v37, |v50|, |v51|
	v_bfe_u32 v48, v20, 16, 1
	v_add3_u32 v32, v24, v44, s10
	v_add3_u32 v34, v18, v46, s10
	v_add3_u32 v35, v19, v47, s10
	v_and_b32_e32 v46, 0xffff0000, v30
	v_and_b32_e32 v47, 0xffff0000, v31
	v_max3_f32 v37, v37, |v52|, |v53|
	v_add3_u32 v36, v20, v48, s10
	v_and_b32_e32 v48, 0xffff0000, v32
	v_and_b32_e32 v49, 0xffff0000, v33
	v_max3_f32 v37, v37, |v46|, |v47|
	v_and_b32_e32 v42, 0xffff0000, v34
	v_and_b32_e32 v43, 0xffff0000, v35
	v_max3_f32 v37, v37, |v48|, |v49|
	v_and_b32_e32 v44, 0xffff0000, v36
	v_max3_f32 v37, v37, |v42|, |v43|
	v_and_b32_e32 v38, 0xffff0000, v38
	v_and_b32_e32 v39, 0xffff0000, v39
	v_max3_f32 v37, v37, |v44|, |v45|
	v_and_b32_e32 v40, 0xffff0000, v40
	v_and_b32_e32 v41, 0xffff0000, v41
	v_max3_f32 v37, v37, |v38|, |v39|
	v_and_b32_e32 v33, 0xffff0000, v79
	v_and_b32_e32 v34, 0xffff0000, v147
	v_max3_f32 v37, v37, |v40|, |v41|
	v_and_b32_e32 v35, 0xffff0000, v148
	v_and_b32_e32 v36, 0xffff0000, v149
	v_max3_f32 v37, v37, |v33|, |v34|
	v_and_b32_e32 v29, 0xffff0000, v150
	v_and_b32_e32 v30, 0xffff0000, v151
	v_max3_f32 v37, v37, |v35|, |v36|
	v_and_b32_e32 v31, 0xffff0000, v152
	v_and_b32_e32 v32, 0xffff0000, v153
	v_max3_f32 v37, v37, |v29|, |v30|
	v_bfe_u32 v83, v100, 16, 1
	v_bfe_u32 v123, v101, 16, 1
	global_store_dwordx4 v130, v[2:5], s[8:9] offset:1024
	v_cvt_pk_bf16_f32 v80, v22, v23
	v_cvt_pk_bf16_f32 v81, v24, v25
	v_and_b32_e32 v25, 0xffff0000, v154
	v_and_b32_e32 v26, 0xffff0000, v155
	v_max3_f32 v37, v37, |v31|, |v32|
	v_bfe_u32 v124, v102, 16, 1
	v_bfe_u32 v125, v103, 16, 1
	v_add3_u32 v158, v100, v83, s10
	v_add3_u32 v123, v101, v123, s10
	v_and_b32_e32 v27, 0xffff0000, v156
	v_and_b32_e32 v28, 0xffff0000, v157
	v_max3_f32 v37, v37, |v25|, |v26|
	v_bfe_u32 v126, v104, 16, 1
	v_bfe_u32 v127, v105, 16, 1
	v_add3_u32 v124, v102, v124, s10
	v_add3_u32 v125, v103, v125, s10
	v_cvt_pk_bf16_f32 v82, v18, v19
	v_cvt_pk_bf16_f32 v83, v20, v21
	v_and_b32_e32 v21, 0xffff0000, v158
	v_and_b32_e32 v22, 0xffff0000, v123
	v_max3_f32 v37, v37, |v27|, |v28|
	v_bfe_u32 v128, v106, 16, 1
	v_bfe_u32 v129, v107, 16, 1
	v_add3_u32 v126, v104, v126, s10
	v_add3_u32 v127, v105, v127, s10
	v_and_b32_e32 v23, 0xffff0000, v124
	v_and_b32_e32 v24, 0xffff0000, v125
	v_max3_f32 v37, v37, |v21|, |v22|
	v_bfe_u32 v131, v108, 16, 1
	v_bfe_u32 v132, v109, 16, 1
	v_add3_u32 v128, v106, v128, s10
	v_add3_u32 v129, v107, v129, s10
	v_and_b32_e32 v17, 0xffff0000, v126
	v_and_b32_e32 v18, 0xffff0000, v127
	v_max3_f32 v37, v37, |v23|, |v24|
	v_bfe_u32 v133, v110, 16, 1
	v_bfe_u32 v134, v111, 16, 1
	v_add3_u32 v131, v108, v131, s10
	v_add3_u32 v132, v109, v132, s10
	v_and_b32_e32 v19, 0xffff0000, v128
	v_and_b32_e32 v20, 0xffff0000, v129
	v_max3_f32 v37, v37, |v17|, |v18|
	v_bfe_u32 v135, v112, 16, 1
	v_bfe_u32 v136, v113, 16, 1
	v_add3_u32 v133, v110, v133, s10
	v_add3_u32 v134, v111, v134, s10
	v_and_b32_e32 v13, 0xffff0000, v131
	v_and_b32_e32 v14, 0xffff0000, v132
	v_max3_f32 v37, v37, |v19|, |v20|
	v_bfe_u32 v137, v114, 16, 1
	v_bfe_u32 v138, v115, 16, 1
	v_add3_u32 v135, v112, v135, s10
	v_add3_u32 v136, v113, v136, s10
	v_and_b32_e32 v15, 0xffff0000, v133
	v_and_b32_e32 v16, 0xffff0000, v134
	v_max3_f32 v37, v37, |v13|, |v14|
	v_bfe_u32 v139, v116, 16, 1
	v_bfe_u32 v140, v117, 16, 1
	v_add3_u32 v137, v114, v137, s10
	v_add3_u32 v138, v115, v138, s10
	v_and_b32_e32 v9, 0xffff0000, v135
	v_and_b32_e32 v10, 0xffff0000, v136
	v_max3_f32 v37, v37, |v15|, |v16|
	v_bfe_u32 v141, v118, 16, 1
	v_bfe_u32 v142, v119, 16, 1
	v_add3_u32 v139, v116, v139, s10
	v_add3_u32 v140, v117, v140, s10
	v_and_b32_e32 v11, 0xffff0000, v137
	v_and_b32_e32 v12, 0xffff0000, v138
	v_max3_f32 v37, v37, |v9|, |v10|
	v_bfe_u32 v143, v120, 16, 1
	v_bfe_u32 v144, v121, 16, 1
	v_add3_u32 v141, v118, v141, s10
	v_add3_u32 v142, v119, v142, s10
	v_and_b32_e32 v5, 0xffff0000, v139
	v_and_b32_e32 v6, 0xffff0000, v140
	v_max3_f32 v37, v37, |v11|, |v12|
	v_bfe_u32 v145, v122, 16, 1
	v_bfe_u32 v146, v68, 16, 1
	v_add3_u32 v143, v120, v143, s10
	v_add3_u32 v144, v121, v144, s10
	v_and_b32_e32 v7, 0xffff0000, v141
	v_and_b32_e32 v8, 0xffff0000, v142
	v_max3_f32 v37, v37, |v5|, |v6|
	v_add3_u32 v145, v122, v145, s10
	v_add3_u32 v146, v68, v146, s10
	v_and_b32_e32 v2, 0xffff0000, v143
	v_and_b32_e32 v3, 0xffff0000, v144
	v_max3_f32 v37, v37, |v7|, |v8|
	v_and_b32_e32 v4, 0xffff0000, v145
	v_max3_f32 v79, v37, |v2|, |v3|
	v_and_b32_e32 v37, 0xffff0000, v146
	v_max3_f32 v79, v79, |v4|, |v37|
	ds_bpermute_b32 v73, v73, v79
	global_store_dwordx4 v130, v[80:83], s[8:9] offset:2048
	v_cmp_eq_u32_e32 vcc, 0, v1
	s_waitcnt lgkmcnt(0)
	v_max_f32_e32 v73, v73, v73
	v_max_f32_e32 v73, v79, v73
	v_cvt_pk_bf16_f32 v80, v84, v85
	ds_bpermute_b32 v84, v78, v73
	v_cvt_pk_bf16_f32 v81, v86, v87
	v_cvt_pk_bf16_f32 v82, v88, v89
	v_cvt_pk_bf16_f32 v83, v90, v91
	global_store_dwordx4 v130, v[80:83], s[8:9] offset:3072
	s_nop 1
	v_cvt_pk_bf16_f32 v80, v92, v93
	v_cvt_pk_bf16_f32 v81, v94, v95
	v_cvt_pk_bf16_f32 v82, v96, v97
	v_cvt_pk_bf16_f32 v83, v98, v99
	global_store_dwordx4 v72, v[80:83], s[8:9]
	s_waitcnt lgkmcnt(0)
	v_max_f32_e32 v72, v84, v84
	v_max_f32_e32 v72, v73, v72
	ds_bpermute_b32 v73, v77, v72
	v_cvt_pk_bf16_f32 v78, v100, v101
	v_cvt_pk_bf16_f32 v79, v102, v103
	v_cvt_pk_bf16_f32 v80, v104, v105
	v_cvt_pk_bf16_f32 v81, v106, v107
	global_store_dwordx4 v71, v[78:81], s[8:9]
	s_waitcnt lgkmcnt(0)
	v_max_f32_e32 v71, v73, v73
	v_max_f32_e32 v71, v72, v71
	ds_bpermute_b32 v72, v76, v71
	v_cvt_pk_bf16_f32 v78, v108, v109
	v_cvt_pk_bf16_f32 v79, v110, v111
	v_cvt_pk_bf16_f32 v80, v112, v113
	v_cvt_pk_bf16_f32 v81, v114, v115
	s_waitcnt lgkmcnt(0)
	v_max_f32_e32 v72, v72, v72
	v_max_f32_e32 v73, v71, v72
	ds_bpermute_b32 v75, v75, v73
	global_store_dwordx4 v70, v[78:81], s[8:9]
	v_cvt_pk_bf16_f32 v70, v116, v117
	v_cvt_pk_bf16_f32 v71, v118, v119
	v_cvt_pk_bf16_f32 v72, v120, v121
	s_waitcnt lgkmcnt(0)
	v_max_f32_e32 v75, v75, v75
	v_max_f32_e32 v75, v73, v75
	ds_bpermute_b32 v74, v74, v75
	v_cvt_pk_bf16_f32 v73, v122, v68
	v_lshlrev_b32_e32 v68, 1, v69
	global_store_dwordx4 v68, v[70:73], s[8:9]
	s_waitcnt lgkmcnt(0)
	v_max_f32_e32 v1, v74, v74
	v_max_f32_e32 v1, v75, v1
	s_and_saveexec_b64 s[0:1], vcc
	s_cbranch_execz .LBB0_782
	s_lshl_b64 s[4:5], s[6:7], 2
	s_add_u32 s4, s53, s4
	v_mul_f32_e32 v68, 0x3c010204, v1
	s_addc_u32 s5, s54, s5
	global_store_dword v67, v68, s[4:5]

.LBB0_1181:
	s_cmp_lt_i32 s6, 32
	s_cbranch_scc0 .LBB0_1183
	s_ashr_i32 s7, s6, 31
	s_lshl_b64 s[0:1], s[6:7], 14
	s_waitcnt lgkmcnt(0)
	s_add_u32 s2, s4, s0
	s_addc_u32 s3, s5, s1
	s_add_u32 s0, s2, 0x69ac0000
	s_addc_u32 s1, s3, 0
	global_load_dwordx4 v[2:5], v130, s[0:1]
	v_lshlrev_b32_e32 v38, 3, v1
	v_or_b32_e32 v67, 0xe00, v38
	v_lshlrev_b32_e32 v68, 2, v67
	global_load_dwordx4 v[26:29], v68, s[0:1] offset:16
	global_load_dwordx4 v[6:9], v130, s[0:1] offset:16
	global_load_dwordx4 v[14:17], v130, s[0:1] offset:2048
	global_load_dwordx4 v[10:13], v130, s[0:1] offset:2064
	v_or_b32_e32 v77, 0x1000, v130
	global_load_dwordx4 v[22:25], v77, s[0:1]
	global_load_dwordx4 v[18:21], v77, s[0:1] offset:16
	v_or_b32_e32 v98, 0x1800, v130
	global_load_dwordx4 v[34:37], v98, s[0:1]
	global_load_dwordx4 v[30:33], v98, s[0:1] offset:16
	v_or_b32_e32 v71, 0x800, v38
	v_lshlrev_b32_e32 v99, 2, v71
	global_load_dwordx4 v[54:57], v99, s[0:1]
	global_load_dwordx4 v[50:53], v99, s[0:1] offset:16
	v_or_b32_e32 v70, 0xa00, v38
	v_lshlrev_b32_e32 v100, 2, v70
	global_load_dwordx4 v[62:65], v100, s[0:1]
	global_load_dwordx4 v[58:61], v100, s[0:1] offset:16
	v_or_b32_e32 v69, 0xc00, v38
	v_lshlrev_b32_e32 v76, 2, v69
	global_load_dwordx4 v[46:49], v76, s[0:1]
	global_load_dwordx4 v[42:45], v76, s[0:1] offset:16
	global_load_dwordx4 v[38:41], v68, s[0:1]
	s_add_u32 s2, s2, 0x69b40000
	s_addc_u32 s3, s3, 0
	global_load_dwordx4 v[78:81], v130, s[8:9] offset:16
	global_load_dwordx4 v[82:85], v130, s[8:9]
	global_load_dwordx4 v[86:89], v130, s[2:3] offset:16
	global_load_dwordx4 v[90:93], v130, s[2:3]
	global_load_dwordx4 v[146:149], v130, s[8:9] offset:2048
	global_load_dwordx4 v[154:157], v130, s[2:3] offset:2048
	global_load_dwordx4 v[178:181], v130, s[2:3] offset:2064
	global_load_dwordx4 v[182:185], v130, s[8:9] offset:2064
	global_load_dwordx4 v[186:189], v77, s[8:9]
	global_load_dwordx4 v[190:193], v77, s[2:3]
	global_load_dwordx4 v[194:197], v77, s[2:3] offset:16
	global_load_dwordx4 v[198:201], v77, s[8:9] offset:16
	global_load_dwordx4 v[202:205], v98, s[8:9]
	global_load_dwordx4 v[206:209], v98, s[2:3]
	global_load_dwordx4 v[210:213], v98, s[2:3] offset:16
	global_load_dwordx4 v[214:217], v98, s[8:9] offset:16
	global_load_dwordx4 v[218:221], v99, s[8:9]
	global_load_dwordx4 v[222:225], v99, s[2:3]
	global_load_dwordx4 v[226:229], v99, s[2:3] offset:16
	global_load_dwordx4 v[230:233], v99, s[8:9] offset:16
	global_load_dwordx4 v[236:239], v100, s[8:9]
	global_load_dwordx4 v[240:243], v100, s[2:3]
	global_load_dwordx4 v[244:247], v100, s[2:3] offset:16
	global_load_dwordx4 v[248:251], v100, s[8:9] offset:16
	v_mbcnt_hi_u32_b32 v66, -1, v234
	v_and_b32_e32 v72, 64, v66
	v_xor_b32_e32 v73, 1, v66
	v_add_u32_e32 v74, 64, v72
	v_cmp_lt_i32_e32 vcc, v73, v74
	s_mov_b32 s10, 0xf800000
	v_lshlrev_b32_e32 v1, 4, v1
	v_cndmask_b32_e32 v72, v66, v73, vcc
	v_lshlrev_b32_e32 v75, 2, v72
	v_lshlrev_b32_e32 v71, 1, v71
	v_lshlrev_b32_e32 v70, 1, v70
	v_lshlrev_b32_e32 v69, 1, v69
	s_waitcnt vmcnt(39)
	v_mul_f32_e32 v94, v3, v3
	v_fmac_f32_e32 v94, v2, v2
	v_fmac_f32_e32 v94, v4, v4
	v_fmac_f32_e32 v94, v5, v5
	s_waitcnt vmcnt(37)
	v_fmac_f32_e32 v94, v6, v6
	v_fmac_f32_e32 v94, v7, v7
	v_fmac_f32_e32 v94, v8, v8
	v_fmac_f32_e32 v94, v9, v9
	s_waitcnt vmcnt(36)
	v_fmac_f32_e32 v94, v14, v14
	v_fmac_f32_e32 v94, v15, v15
	v_fmac_f32_e32 v94, v16, v16
	v_fmac_f32_e32 v94, v17, v17
	s_waitcnt vmcnt(35)
	v_fmac_f32_e32 v94, v10, v10
	v_fmac_f32_e32 v94, v11, v11
	v_fmac_f32_e32 v94, v12, v12
	v_fmac_f32_e32 v94, v13, v13
	s_waitcnt vmcnt(34)
	v_fmac_f32_e32 v94, v22, v22
	v_fmac_f32_e32 v94, v23, v23
	v_fmac_f32_e32 v94, v24, v24
	v_fmac_f32_e32 v94, v25, v25
	s_waitcnt vmcnt(33)
	v_fmac_f32_e32 v94, v18, v18
	v_fmac_f32_e32 v94, v19, v19
	v_fmac_f32_e32 v94, v20, v20
	v_fmac_f32_e32 v94, v21, v21
	s_waitcnt vmcnt(32)
	v_fmac_f32_e32 v94, v34, v34
	v_fmac_f32_e32 v94, v35, v35
	v_fmac_f32_e32 v94, v36, v36
	v_fmac_f32_e32 v94, v37, v37
	s_waitcnt vmcnt(31)
	v_fmac_f32_e32 v94, v30, v30
	v_fmac_f32_e32 v94, v31, v31
	v_fmac_f32_e32 v94, v32, v32
	v_fmac_f32_e32 v94, v33, v33
	s_waitcnt vmcnt(30)
	v_fmac_f32_e32 v94, v54, v54
	v_fmac_f32_e32 v94, v55, v55
	v_fmac_f32_e32 v94, v56, v56
	v_fmac_f32_e32 v94, v57, v57
	s_waitcnt vmcnt(29)
	v_fmac_f32_e32 v94, v50, v50
	v_fmac_f32_e32 v94, v51, v51
	v_fmac_f32_e32 v94, v52, v52
	v_fmac_f32_e32 v94, v53, v53
	s_waitcnt vmcnt(28)
	v_fmac_f32_e32 v94, v62, v62
	v_fmac_f32_e32 v94, v63, v63
	v_fmac_f32_e32 v94, v64, v64
	v_fmac_f32_e32 v94, v65, v65
	s_waitcnt vmcnt(27)
	v_fmac_f32_e32 v94, v58, v58
	v_fmac_f32_e32 v94, v59, v59
	v_fmac_f32_e32 v94, v60, v60
	v_fmac_f32_e32 v94, v61, v61
	s_waitcnt vmcnt(26)
	v_fmac_f32_e32 v94, v46, v46
	v_fmac_f32_e32 v94, v47, v47
	v_fmac_f32_e32 v94, v48, v48
	v_fmac_f32_e32 v94, v49, v49
	s_waitcnt vmcnt(25)
	v_fmac_f32_e32 v94, v42, v42
	v_fmac_f32_e32 v94, v43, v43
	v_fmac_f32_e32 v94, v44, v44
	v_fmac_f32_e32 v94, v45, v45
	s_waitcnt vmcnt(24)
	v_fmac_f32_e32 v94, v38, v38
	v_fmac_f32_e32 v94, v39, v39
	v_fmac_f32_e32 v94, v40, v40
	v_fmac_f32_e32 v94, v41, v41
	v_fmac_f32_e32 v94, v26, v26
	v_pk_mul_f32 v[72:73], v[28:29], v[28:29]
	v_fmac_f32_e32 v94, v27, v27
	v_add_f32_e32 v72, v72, v94
	v_add_f32_e32 v72, v73, v72
	ds_bpermute_b32 v73, v75, v72
	v_xor_b32_e32 v94, 2, v66
	v_cmp_lt_i32_e32 vcc, v94, v74
	s_waitcnt lgkmcnt(0)
	v_add_f32_e32 v72, v72, v73
	v_cndmask_b32_e32 v94, v66, v94, vcc
	v_lshlrev_b32_e32 v118, 2, v94
	ds_bpermute_b32 v73, v118, v72
	v_xor_b32_e32 v94, 4, v66
	v_cmp_lt_i32_e32 vcc, v94, v74
	s_waitcnt lgkmcnt(0)
	v_add_f32_e32 v72, v72, v73
	v_cndmask_b32_e32 v94, v66, v94, vcc
	v_lshlrev_b32_e32 v119, 2, v94
	ds_bpermute_b32 v73, v119, v72
	v_xor_b32_e32 v94, 8, v66
	v_cmp_lt_i32_e32 vcc, v94, v74
	s_waitcnt lgkmcnt(0)
	v_add_f32_e32 v72, v72, v73
	v_cndmask_b32_e32 v94, v66, v94, vcc
	v_lshlrev_b32_e32 v120, 2, v94
	ds_bpermute_b32 v73, v120, v72
	v_xor_b32_e32 v94, 16, v66
	v_cmp_lt_i32_e32 vcc, v94, v74
	s_waitcnt lgkmcnt(0)
	v_add_f32_e32 v72, v72, v73
	v_cndmask_b32_e32 v94, v66, v94, vcc
	v_lshlrev_b32_e32 v121, 2, v94
	ds_bpermute_b32 v73, v121, v72
	v_xor_b32_e32 v94, 32, v66
	v_cmp_lt_i32_e32 vcc, v94, v74
	s_nop 1
	v_cndmask_b32_e32 v66, v66, v94, vcc
	v_lshlrev_b32_e32 v74, 2, v66
	s_waitcnt lgkmcnt(0)
	v_add_f32_e32 v66, v72, v73
	ds_bpermute_b32 v72, v74, v66
	v_mov_b32_e32 v73, 0x358637bd
	s_waitcnt lgkmcnt(0)
	v_add_f32_e32 v66, v66, v72
	v_fmamk_f32 v66, v66, 0x39800000, v73
	v_mul_f32_e32 v72, 0x4f800000, v66
	v_cmp_gt_f32_e32 vcc, s10, v66
	s_nop 1
	v_cndmask_b32_e32 v66, v66, v72, vcc
	v_sqrt_f32_e32 v94, v66
	v_mov_b32_e32 v72, 0x260
	v_add_u32_e32 v95, -1, v94
	v_add_u32_e32 v96, 1, v94
	v_fma_f32 v97, -v95, v94, v66
	v_fma_f32 v101, -v96, v94, v66
	v_cmp_ge_f32_e64 s[0:1], 0, v97
	s_nop 1
	v_cndmask_b32_e64 v94, v94, v95, s[0:1]
	v_cmp_lt_f32_e64 s[0:1], 0, v101
	s_nop 1
	v_cndmask_b32_e64 v94, v94, v96, s[0:1]
	v_mul_f32_e32 v95, 0x37800000, v94
	v_cndmask_b32_e32 v94, v94, v95, vcc
	v_cmp_class_f32_e32 vcc, v66, v72
	s_nop 1
	v_cndmask_b32_e32 v66, v94, v66, vcc
	v_div_scale_f32 v94, s[0:1], v66, v66, 1.0
	v_rcp_f32_e32 v95, v94
	v_div_scale_f32 v96, vcc, 1.0, v66, 1.0
	s_lshl_b64 s[0:1], s[6:7], 13
	v_fma_f32 v97, -v94, v95, 1.0
	v_fmac_f32_e32 v95, v97, v95
	v_mul_f32_e32 v97, v96, v95
	v_fma_f32 v101, -v94, v97, v96
	v_fmac_f32_e32 v97, v101, v95
	v_fma_f32 v94, -v94, v97, v96
	v_div_fmas_f32 v94, v94, v95, v97
	v_div_fixup_f32 v66, v94, v66, 1.0
	v_pk_mul_f32 v[2:3], v[2:3], v[66:67] op_sel_hi:[1,0]
	v_pk_mul_f32 v[4:5], v[4:5], v[66:67] op_sel_hi:[1,0]
	v_pk_mul_f32 v[94:95], v[6:7], v[66:67] op_sel_hi:[1,0]
	v_pk_mul_f32 v[96:97], v[8:9], v[66:67] op_sel_hi:[1,0]
	s_waitcnt vmcnt(20)
	v_pk_fma_f32 v[6:7], v[82:83], v[2:3], v[90:91]
	v_pk_fma_f32 v[8:9], v[84:85], v[4:5], v[92:93]
	v_pk_fma_f32 v[2:3], v[78:79], v[94:95], v[86:87]
	v_pk_fma_f32 v[4:5], v[80:81], v[96:97], v[88:89]
	global_store_dwordx4 v130, v[6:9], s[2:3]
	global_store_dwordx4 v130, v[2:5], s[2:3] offset:16
	s_nop 1
	s_waitcnt vmcnt(21)
	v_mov_b64_e32 v[78:79], v[146:147]
	v_mov_b64_e32 v[80:81], v[148:149]
	s_waitcnt vmcnt(20)
	v_mov_b64_e32 v[82:83], v[154:155]
	v_mov_b64_e32 v[84:85], v[156:157]
	s_waitcnt vmcnt(19)
	v_mov_b64_e32 v[86:87], v[178:179]
	v_mov_b64_e32 v[88:89], v[180:181]
	s_waitcnt vmcnt(18)
	v_mov_b64_e32 v[90:91], v[182:183]
	v_mov_b64_e32 v[92:93], v[184:185]
	v_pk_mul_f32 v[14:15], v[14:15], v[66:67] op_sel_hi:[1,0]
	v_pk_mul_f32 v[16:17], v[16:17], v[66:67] op_sel_hi:[1,0]
	v_pk_mul_f32 v[10:11], v[10:11], v[66:67] op_sel_hi:[1,0]
	v_pk_mul_f32 v[12:13], v[12:13], v[66:67] op_sel_hi:[1,0]
	v_pk_mul_f32 v[22:23], v[22:23], v[66:67] op_sel_hi:[1,0]
	v_pk_mul_f32 v[24:25], v[24:25], v[66:67] op_sel_hi:[1,0]
	v_pk_mul_f32 v[18:19], v[18:19], v[66:67] op_sel_hi:[1,0]
	v_pk_mul_f32 v[20:21], v[20:21], v[66:67] op_sel_hi:[1,0]
	v_pk_mul_f32 v[34:35], v[34:35], v[66:67] op_sel_hi:[1,0]
	v_pk_mul_f32 v[36:37], v[36:37], v[66:67] op_sel_hi:[1,0]
	v_pk_mul_f32 v[30:31], v[30:31], v[66:67] op_sel_hi:[1,0]
	v_pk_mul_f32 v[32:33], v[32:33], v[66:67] op_sel_hi:[1,0]
	v_pk_mul_f32 v[54:55], v[54:55], v[66:67] op_sel_hi:[1,0]
	v_pk_mul_f32 v[56:57], v[56:57], v[66:67] op_sel_hi:[1,0]
	v_pk_mul_f32 v[50:51], v[50:51], v[66:67] op_sel_hi:[1,0]
	v_pk_mul_f32 v[52:53], v[52:53], v[66:67] op_sel_hi:[1,0]
	v_pk_mul_f32 v[62:63], v[62:63], v[66:67] op_sel_hi:[1,0]
	v_pk_mul_f32 v[64:65], v[64:65], v[66:67] op_sel_hi:[1,0]
	v_pk_mul_f32 v[58:59], v[58:59], v[66:67] op_sel_hi:[1,0]
	v_pk_mul_f32 v[60:61], v[60:61], v[66:67] op_sel_hi:[1,0]
	v_pk_mul_f32 v[46:47], v[46:47], v[66:67] op_sel_hi:[1,0]
	v_pk_mul_f32 v[48:49], v[48:49], v[66:67] op_sel_hi:[1,0]
	v_pk_mul_f32 v[42:43], v[42:43], v[66:67] op_sel_hi:[1,0]
	v_pk_mul_f32 v[44:45], v[44:45], v[66:67] op_sel_hi:[1,0]
	v_pk_mul_f32 v[102:103], v[38:39], v[66:67] op_sel_hi:[1,0]
	v_pk_mul_f32 v[104:105], v[40:41], v[66:67] op_sel_hi:[1,0]
	v_pk_mul_f32 v[106:107], v[26:27], v[66:67] op_sel_hi:[1,0]
	v_pk_mul_f32 v[108:109], v[28:29], v[66:67] op_sel_hi:[1,0]
	v_pk_mul_f32 v[110:111], v[6:7], v[6:7]
	v_pk_mul_f32 v[112:113], v[8:9], v[8:9]
	v_add_f32_e32 v66, v110, v111
	v_add_f32_e32 v66, v112, v66
	v_pk_mul_f32 v[114:115], v[2:3], v[2:3]
	v_add_f32_e32 v66, v113, v66
	v_add_f32_e32 v66, v114, v66
	v_pk_mul_f32 v[116:117], v[4:5], v[4:5]
	v_add_f32_e32 v66, v115, v66
	v_add_f32_e32 v66, v116, v66
	v_add_f32_e32 v66, v117, v66
	s_add_u32 s0, s4, s0
	s_addc_u32 s1, s5, s1
	s_add_u32 s4, s0, 0x69900000
	s_addc_u32 s5, s1, 0
	v_pk_fma_f32 v[14:15], v[78:79], v[14:15], v[82:83]
	v_pk_fma_f32 v[16:17], v[80:81], v[16:17], v[84:85]
	v_pk_fma_f32 v[10:11], v[90:91], v[10:11], v[86:87]
	v_pk_fma_f32 v[12:13], v[92:93], v[12:13], v[88:89]
	global_store_dwordx4 v130, v[14:17], s[2:3] offset:2048
	global_store_dwordx4 v130, v[10:13], s[2:3] offset:2064
	s_nop 1
	s_waitcnt vmcnt(19)
	v_mov_b64_e32 v[78:79], v[186:187]
	v_mov_b64_e32 v[80:81], v[188:189]
	s_waitcnt vmcnt(18)
	v_mov_b64_e32 v[82:83], v[190:191]
	v_mov_b64_e32 v[84:85], v[192:193]
	s_waitcnt vmcnt(17)
	v_mov_b64_e32 v[86:87], v[194:195]
	v_mov_b64_e32 v[88:89], v[196:197]
	s_waitcnt vmcnt(16)
	v_mov_b64_e32 v[90:91], v[198:199]
	v_mov_b64_e32 v[92:93], v[200:201]
	v_pk_fma_f32 v[22:23], v[78:79], v[22:23], v[82:83]
	v_pk_fma_f32 v[24:25], v[80:81], v[24:25], v[84:85]
	v_pk_fma_f32 v[18:19], v[90:91], v[18:19], v[86:87]
	v_pk_fma_f32 v[20:21], v[92:93], v[20:21], v[88:89]
	global_store_dwordx4 v77, v[22:25], s[2:3]
	global_store_dwordx4 v77, v[18:21], s[2:3] offset:16
	s_nop 1
	s_waitcnt vmcnt(17)
	v_mov_b64_e32 v[78:79], v[202:203]
	v_mov_b64_e32 v[80:81], v[204:205]
	s_waitcnt vmcnt(16)
	v_mov_b64_e32 v[82:83], v[206:207]
	v_mov_b64_e32 v[84:85], v[208:209]
	s_waitcnt vmcnt(15)
	v_mov_b64_e32 v[86:87], v[210:211]
	v_mov_b64_e32 v[88:89], v[212:213]
	s_waitcnt vmcnt(14)
	v_mov_b64_e32 v[90:91], v[214:215]
	v_mov_b64_e32 v[92:93], v[216:217]
	v_pk_fma_f32 v[34:35], v[78:79], v[34:35], v[82:83]
	v_pk_fma_f32 v[36:37], v[80:81], v[36:37], v[84:85]
	v_pk_fma_f32 v[30:31], v[90:91], v[30:31], v[86:87]
	v_pk_fma_f32 v[32:33], v[92:93], v[32:33], v[88:89]
	global_store_dwordx4 v98, v[34:37], s[2:3]
	global_store_dwordx4 v98, v[30:33], s[2:3] offset:16
	s_nop 1
	s_waitcnt vmcnt(15)
	v_mov_b64_e32 v[78:79], v[218:219]
	v_mov_b64_e32 v[80:81], v[220:221]
	s_waitcnt vmcnt(14)
	v_mov_b64_e32 v[82:83], v[222:223]
	v_mov_b64_e32 v[84:85], v[224:225]
	s_waitcnt vmcnt(13)
	v_mov_b64_e32 v[86:87], v[226:227]
	v_mov_b64_e32 v[88:89], v[228:229]
	s_waitcnt vmcnt(12)
	v_mov_b64_e32 v[90:91], v[230:231]
	v_mov_b64_e32 v[92:93], v[232:233]
	v_pk_fma_f32 v[54:55], v[78:79], v[54:55], v[82:83]
	v_pk_fma_f32 v[56:57], v[80:81], v[56:57], v[84:85]
	v_pk_fma_f32 v[50:51], v[90:91], v[50:51], v[86:87]
	v_pk_fma_f32 v[52:53], v[92:93], v[52:53], v[88:89]
	global_store_dwordx4 v99, v[54:57], s[2:3]
	global_store_dwordx4 v99, v[50:53], s[2:3] offset:16
	s_nop 1
	s_waitcnt vmcnt(13)
	v_mov_b64_e32 v[78:79], v[236:237]
	v_mov_b64_e32 v[80:81], v[238:239]
	s_waitcnt vmcnt(12)
	v_mov_b64_e32 v[82:83], v[240:241]
	v_mov_b64_e32 v[84:85], v[242:243]
	s_waitcnt vmcnt(11)
	v_mov_b64_e32 v[86:87], v[244:245]
	v_mov_b64_e32 v[88:89], v[246:247]
	s_waitcnt vmcnt(10)
	v_mov_b64_e32 v[90:91], v[248:249]
	v_mov_b64_e32 v[92:93], v[250:251]
	v_pk_fma_f32 v[62:63], v[78:79], v[62:63], v[82:83]
	v_pk_fma_f32 v[64:65], v[80:81], v[64:65], v[84:85]
	v_pk_fma_f32 v[58:59], v[90:91], v[58:59], v[86:87]
	v_pk_fma_f32 v[60:61], v[92:93], v[60:61], v[88:89]
	global_store_dwordx4 v100, v[62:65], s[2:3]
	global_store_dwordx4 v100, v[58:61], s[2:3] offset:16
	global_load_dwordx4 v[78:81], v76, s[8:9]
	global_load_dwordx4 v[82:85], v76, s[2:3]
	global_load_dwordx4 v[86:89], v76, s[2:3] offset:16
	global_load_dwordx4 v[90:93], v76, s[8:9] offset:16
	global_load_dwordx4 v[94:97], v68, s[2:3] offset:16
	global_load_dwordx4 v[98:101], v68, s[2:3]
	s_waitcnt vmcnt(4)
	v_pk_fma_f32 v[38:39], v[78:79], v[46:47], v[82:83]
	v_pk_fma_f32 v[40:41], v[80:81], v[48:49], v[84:85]
	s_waitcnt vmcnt(2)
	v_pk_fma_f32 v[26:27], v[90:91], v[42:43], v[86:87]
	v_pk_fma_f32 v[28:29], v[92:93], v[44:45], v[88:89]
	global_store_dwordx4 v76, v[38:41], s[2:3]
	global_store_dwordx4 v76, v[26:29], s[2:3] offset:16
	global_load_dwordx4 v[42:45], v68, s[8:9] offset:16
	global_load_dwordx4 v[46:49], v68, s[8:9]
	v_pk_mul_f32 v[76:77], v[14:15], v[14:15]
	v_pk_mul_f32 v[78:79], v[16:17], v[16:17]
	v_add_f32_e32 v66, v76, v66
	v_add_f32_e32 v66, v77, v66
	v_add_f32_e32 v66, v78, v66
	v_pk_mul_f32 v[80:81], v[10:11], v[10:11]
	v_add_f32_e32 v66, v79, v66
	v_add_f32_e32 v66, v80, v66
	v_pk_mul_f32 v[82:83], v[12:13], v[12:13]
	v_add_f32_e32 v66, v81, v66
	v_add_f32_e32 v66, v82, v66
	v_add_f32_e32 v66, v83, v66
	v_pk_mul_f32 v[76:77], v[22:23], v[22:23]
	v_pk_mul_f32 v[78:79], v[24:25], v[24:25]
	v_add_f32_e32 v66, v76, v66
	v_add_f32_e32 v66, v77, v66
	v_add_f32_e32 v66, v78, v66
	v_pk_mul_f32 v[80:81], v[18:19], v[18:19]
	v_add_f32_e32 v66, v79, v66
	v_add_f32_e32 v66, v80, v66
	v_pk_mul_f32 v[82:83], v[20:21], v[20:21]
	v_add_f32_e32 v66, v81, v66
	v_add_f32_e32 v66, v82, v66
	v_add_f32_e32 v66, v83, v66
	v_pk_mul_f32 v[76:77], v[34:35], v[34:35]
	v_pk_mul_f32 v[78:79], v[36:37], v[36:37]
	v_add_f32_e32 v66, v76, v66
	v_add_f32_e32 v66, v77, v66
	v_add_f32_e32 v66, v78, v66
	v_pk_mul_f32 v[80:81], v[30:31], v[30:31]
	v_add_f32_e32 v66, v79, v66
	v_add_f32_e32 v66, v80, v66
	v_pk_mul_f32 v[82:83], v[32:33], v[32:33]
	v_add_f32_e32 v66, v81, v66
	v_add_f32_e32 v66, v82, v66
	v_add_f32_e32 v66, v83, v66
	v_pk_mul_f32 v[76:77], v[54:55], v[54:55]
	v_pk_mul_f32 v[78:79], v[56:57], v[56:57]
	v_add_f32_e32 v66, v76, v66
	v_add_f32_e32 v66, v77, v66
	v_add_f32_e32 v66, v78, v66
	v_pk_mul_f32 v[80:81], v[50:51], v[50:51]
	v_add_f32_e32 v66, v79, v66
	v_add_f32_e32 v66, v80, v66
	v_pk_mul_f32 v[82:83], v[52:53], v[52:53]
	v_add_f32_e32 v66, v81, v66
	v_add_f32_e32 v66, v82, v66
	v_add_f32_e32 v66, v83, v66
	v_pk_mul_f32 v[76:77], v[62:63], v[62:63]
	v_pk_mul_f32 v[78:79], v[64:65], v[64:65]
	v_add_f32_e32 v66, v76, v66
	v_add_f32_e32 v66, v77, v66
	v_add_f32_e32 v66, v78, v66
	v_pk_mul_f32 v[80:81], v[58:59], v[58:59]
	v_add_f32_e32 v66, v79, v66
	v_add_f32_e32 v66, v80, v66
	v_pk_mul_f32 v[82:83], v[60:61], v[60:61]
	v_add_f32_e32 v66, v81, v66
	v_add_f32_e32 v66, v82, v66
	v_add_f32_e32 v66, v83, v66
	v_pk_mul_f32 v[76:77], v[38:39], v[38:39]
	v_pk_mul_f32 v[78:79], v[40:41], v[40:41]
	v_add_f32_e32 v66, v76, v66
	v_add_f32_e32 v66, v77, v66
	v_add_f32_e32 v66, v78, v66
	v_pk_mul_f32 v[80:81], v[26:27], v[26:27]
	v_add_f32_e32 v66, v79, v66
	v_add_f32_e32 v66, v80, v66
	v_pk_mul_f32 v[82:83], v[28:29], v[28:29]
	v_add_f32_e32 v66, v81, v66
	v_add_f32_e32 v66, v82, v66
	v_add_f32_e32 v66, v83, v66
	s_waitcnt vmcnt(1)
	v_pk_fma_f32 v[42:43], v[42:43], v[106:107], v[94:95]
	s_waitcnt vmcnt(0)
	v_pk_fma_f32 v[46:47], v[46:47], v[102:103], v[98:99]
	v_pk_fma_f32 v[48:49], v[48:49], v[104:105], v[100:101]
	v_pk_mul_f32 v[76:77], v[46:47], v[46:47]
	v_pk_mul_f32 v[78:79], v[48:49], v[48:49]
	v_add_f32_e32 v66, v76, v66
	v_add_f32_e32 v66, v77, v66
	v_add_f32_e32 v66, v78, v66
	v_pk_mul_f32 v[80:81], v[42:43], v[42:43]
	v_add_f32_e32 v66, v79, v66
	v_pk_fma_f32 v[44:45], v[44:45], v[108:109], v[96:97]
	v_add_f32_e32 v66, v80, v66
	v_pk_mul_f32 v[82:83], v[44:45], v[44:45]
	v_add_f32_e32 v66, v81, v66
	v_add_f32_e32 v66, v82, v66
	v_add_f32_e32 v66, v83, v66
	ds_bpermute_b32 v75, v75, v66
	global_store_dwordx4 v68, v[46:49], s[2:3]
	global_store_dwordx4 v68, v[42:45], s[2:3] offset:16
	s_waitcnt lgkmcnt(0)
	v_add_f32_e32 v66, v66, v75
	ds_bpermute_b32 v75, v118, v66
	s_waitcnt lgkmcnt(0)
	v_add_f32_e32 v66, v66, v75
	ds_bpermute_b32 v75, v119, v66
	s_waitcnt lgkmcnt(0)
	v_add_f32_e32 v66, v66, v75
	ds_bpermute_b32 v75, v120, v66
	s_waitcnt lgkmcnt(0)
	v_add_f32_e32 v66, v66, v75
	ds_bpermute_b32 v75, v121, v66
	s_waitcnt lgkmcnt(0)
	v_add_f32_e32 v66, v66, v75
	ds_bpermute_b32 v74, v74, v66
	s_waitcnt lgkmcnt(0)
	v_add_f32_e32 v66, v66, v74
	v_fmac_f32_e32 v73, 0x39800000, v66
	v_mul_f32_e32 v66, 0x4f800000, v73
	v_cmp_gt_f32_e32 vcc, s10, v73
	s_nop 1
	v_cndmask_b32_e32 v66, v73, v66, vcc
	v_sqrt_f32_e32 v73, v66
	s_nop 0
	v_add_u32_e32 v74, -1, v73
	v_add_u32_e32 v75, 1, v73
	v_fma_f32 v76, -v74, v73, v66
	v_fma_f32 v77, -v75, v73, v66
	v_cmp_ge_f32_e64 s[0:1], 0, v76
	s_nop 1
	v_cndmask_b32_e64 v73, v73, v74, s[0:1]
	v_cmp_lt_f32_e64 s[0:1], 0, v77
	s_nop 1
	v_cndmask_b32_e64 v73, v73, v75, s[0:1]
	v_mul_f32_e32 v74, 0x37800000, v73
	v_cndmask_b32_e32 v73, v73, v74, vcc
	v_cmp_class_f32_e32 vcc, v66, v72
	s_nop 1
	v_cndmask_b32_e32 v66, v73, v66, vcc
	v_div_scale_f32 v72, s[0:1], v66, v66, 1.0
	v_rcp_f32_e32 v73, v72
	v_div_scale_f32 v68, vcc, 1.0, v66, 1.0
	v_fma_f32 v74, -v72, v73, 1.0
	v_fmac_f32_e32 v73, v74, v73
	v_mul_f32_e32 v74, v68, v73
	v_fma_f32 v75, -v72, v74, v68
	v_fmac_f32_e32 v74, v75, v73
	v_fma_f32 v68, -v72, v74, v68
	v_div_fmas_f32 v68, v68, v73, v74
	v_div_fixup_f32 v66, v68, v66, 1.0
	v_mul_f32_e32 v5, v5, v66
	v_mul_f32_e32 v6, v6, v66
	v_mul_f32_e32 v7, v7, v66
	v_mul_f32_e32 v8, v8, v66
	v_mul_f32_e32 v9, v9, v66
	v_mul_f32_e32 v68, v2, v66
	v_mul_f32_e32 v72, v3, v66
	v_mul_f32_e32 v73, v4, v66
	v_cvt_pk_bf16_f32 v2, v6, v7
	v_cvt_pk_bf16_f32 v3, v8, v9
	v_cvt_pk_bf16_f32 v4, v68, v72
	v_cvt_pk_bf16_f32 v5, v73, v5
	v_mul_f32_e32 v14, v14, v66
	v_mul_f32_e32 v15, v15, v66
	v_mul_f32_e32 v16, v16, v66
	v_mul_f32_e32 v17, v17, v66
	v_mul_f32_e32 v10, v10, v66
	v_mul_f32_e32 v11, v11, v66
	v_mul_f32_e32 v12, v12, v66
	v_mul_f32_e32 v13, v13, v66
	global_store_dwordx4 v1, v[2:5], s[4:5]
	v_mul_f32_e32 v22, v22, v66
	v_mul_f32_e32 v23, v23, v66
	v_cvt_pk_bf16_f32 v2, v14, v15
	v_cvt_pk_bf16_f32 v3, v16, v17
	v_cvt_pk_bf16_f32 v4, v10, v11
	v_cvt_pk_bf16_f32 v5, v12, v13
	v_mul_f32_e32 v24, v24, v66
	v_mul_f32_e32 v25, v25, v66
	v_mul_f32_e32 v18, v18, v66
	v_mul_f32_e32 v19, v19, v66
	v_mul_f32_e32 v20, v20, v66
	v_mul_f32_e32 v21, v21, v66
	global_store_dwordx4 v1, v[2:5], s[4:5] offset:1024
	v_mul_f32_e32 v34, v34, v66
	v_mul_f32_e32 v35, v35, v66
	v_cvt_pk_bf16_f32 v2, v22, v23
	v_cvt_pk_bf16_f32 v3, v24, v25
	v_cvt_pk_bf16_f32 v4, v18, v19
	v_cvt_pk_bf16_f32 v5, v20, v21
	v_mul_f32_e32 v36, v36, v66
	v_mul_f32_e32 v37, v37, v66
	v_mul_f32_e32 v30, v30, v66
	v_mul_f32_e32 v31, v31, v66
	v_mul_f32_e32 v32, v32, v66
	v_mul_f32_e32 v33, v33, v66
	global_store_dwordx4 v1, v[2:5], s[4:5] offset:2048
	v_mul_f32_e32 v54, v54, v66
	v_mul_f32_e32 v55, v55, v66
	v_cvt_pk_bf16_f32 v2, v34, v35
	v_cvt_pk_bf16_f32 v3, v36, v37
	v_cvt_pk_bf16_f32 v4, v30, v31
	v_cvt_pk_bf16_f32 v5, v32, v33
	v_mul_f32_e32 v56, v56, v66
	v_mul_f32_e32 v57, v57, v66
	v_mul_f32_e32 v50, v50, v66
	v_mul_f32_e32 v51, v51, v66
	v_mul_f32_e32 v52, v52, v66
	v_mul_f32_e32 v53, v53, v66
	global_store_dwordx4 v1, v[2:5], s[4:5] offset:3072
	v_mul_f32_e32 v62, v62, v66
	v_mul_f32_e32 v63, v63, v66
	v_cvt_pk_bf16_f32 v2, v54, v55
	v_cvt_pk_bf16_f32 v3, v56, v57
	v_cvt_pk_bf16_f32 v4, v50, v51
	v_cvt_pk_bf16_f32 v5, v52, v53
	v_mul_f32_e32 v64, v64, v66
	v_mul_f32_e32 v65, v65, v66
	v_mul_f32_e32 v58, v58, v66
	v_mul_f32_e32 v59, v59, v66
	v_mul_f32_e32 v60, v60, v66
	v_mul_f32_e32 v61, v61, v66
	global_store_dwordx4 v71, v[2:5], s[4:5]
	v_mul_f32_e32 v38, v38, v66
	v_mul_f32_e32 v39, v39, v66
	v_cvt_pk_bf16_f32 v2, v62, v63
	v_cvt_pk_bf16_f32 v3, v64, v65
	v_cvt_pk_bf16_f32 v4, v58, v59
	v_cvt_pk_bf16_f32 v5, v60, v61
	v_mul_f32_e32 v40, v40, v66
	v_mul_f32_e32 v41, v41, v66
	v_mul_f32_e32 v26, v26, v66
	v_mul_f32_e32 v27, v27, v66
	v_mul_f32_e32 v28, v28, v66
	v_mul_f32_e32 v29, v29, v66
	global_store_dwordx4 v70, v[2:5], s[4:5]
	v_lshlrev_b32_e32 v1, 1, v67
	v_mul_f32_e32 v46, v46, v66
	v_cvt_pk_bf16_f32 v2, v38, v39
	v_cvt_pk_bf16_f32 v3, v40, v41
	v_cvt_pk_bf16_f32 v4, v26, v27
	v_cvt_pk_bf16_f32 v5, v28, v29
	v_mul_f32_e32 v47, v47, v66
	v_mul_f32_e32 v48, v48, v66
	v_mul_f32_e32 v49, v49, v66
	v_mul_f32_e32 v42, v42, v66
	v_mul_f32_e32 v43, v43, v66
	v_mul_f32_e32 v44, v44, v66
	v_mul_f32_e32 v45, v45, v66
	global_store_dwordx4 v69, v[2:5], s[4:5]
	s_nop 1
	v_cvt_pk_bf16_f32 v2, v46, v47
	v_cvt_pk_bf16_f32 v3, v48, v49
	v_cvt_pk_bf16_f32 v4, v42, v43
	v_cvt_pk_bf16_f32 v5, v44, v45
	global_store_dwordx4 v1, v[2:5], s[4:5]

.LBB0_1632:
	s_cmp_lt_i32 s6, 32
	v_readlane_b32 s65, v252, 37
	v_readlane_b32 s66, v252, 36
	s_cbranch_scc0 .LBB0_1636
	s_ashr_i32 s7, s6, 31
	s_lshl_b64 s[2:3], s[6:7], 12
	s_lshl_b64 s[0:1], s[6:7], 14
	s_add_u32 s4, s8, s0
	s_addc_u32 s5, s9, s1
	s_add_u32 s0, s4, 0x69ac0000
	s_addc_u32 s1, s5, 0
	v_lshlrev_b32_e32 v102, 5, v1
	global_load_dwordx4 v[2:5], v102, s[0:1]
	v_lshlrev_b32_e32 v66, 3, v1
	v_or_b32_e32 v69, 0xe00, v66
	v_lshlrev_b32_e32 v79, 2, v69
	global_load_dwordx4 v[34:37], v79, s[0:1] offset:16
	global_load_dwordx4 v[6:9], v102, s[0:1] offset:16
	global_load_dwordx4 v[14:17], v102, s[0:1] offset:2048
	global_load_dwordx4 v[10:13], v102, s[0:1] offset:2064
	v_or_b32_e32 v103, 0x1000, v102
	global_load_dwordx4 v[22:25], v103, s[0:1]
	global_load_dwordx4 v[18:21], v103, s[0:1] offset:16
	v_or_b32_e32 v104, 0x1800, v102
	global_load_dwordx4 v[30:33], v104, s[0:1]
	global_load_dwordx4 v[26:29], v104, s[0:1] offset:16
	v_or_b32_e32 v72, 0x800, v66
	v_lshlrev_b32_e32 v105, 2, v72
	global_load_dwordx4 v[42:45], v105, s[0:1]
	global_load_dwordx4 v[38:41], v105, s[0:1] offset:16
	v_or_b32_e32 v71, 0xa00, v66
	v_lshlrev_b32_e32 v106, 2, v71
	global_load_dwordx4 v[62:65], v106, s[0:1]
	global_load_dwordx4 v[58:61], v106, s[0:1] offset:16
	v_or_b32_e32 v70, 0xc00, v66
	v_lshlrev_b32_e32 v67, 2, v70
	global_load_dwordx4 v[54:57], v67, s[0:1]
	global_load_dwordx4 v[50:53], v67, s[0:1] offset:16
	global_load_dwordx4 v[46:49], v79, s[0:1]
	s_add_u32 s4, s4, 0x69b40000
	s_addc_u32 s5, s5, 0
	s_add_u32 s10, s10, 0x4000
	s_addc_u32 s11, s11, 0
	global_load_dwordx4 v[82:85], v102, s[4:5] offset:16
	global_load_dwordx4 v[86:89], v102, s[4:5]
	global_load_dwordx4 v[90:93], v102, s[10:11] offset:16
	global_load_dwordx4 v[94:97], v102, s[10:11]
	global_load_dwordx4 v[178:181], v102, s[4:5] offset:2048
	global_load_dwordx4 v[182:185], v102, s[4:5] offset:2064
	global_load_dwordx4 v[186:189], v103, s[10:11]
	global_load_dwordx4 v[190:193], v103, s[4:5]
	global_load_dwordx4 v[194:197], v103, s[4:5] offset:16
	global_load_dwordx4 v[198:201], v103, s[10:11] offset:16
	global_load_dwordx4 v[202:205], v104, s[10:11]
	global_load_dwordx4 v[206:209], v104, s[4:5]
	global_load_dwordx4 v[210:213], v104, s[4:5] offset:16
	global_load_dwordx4 v[214:217], v104, s[10:11] offset:16
	global_load_dwordx4 v[218:221], v105, s[10:11]
	global_load_dwordx4 v[222:225], v105, s[4:5]
	global_load_dwordx4 v[226:229], v105, s[4:5] offset:16
	global_load_dwordx4 v[230:233], v105, s[10:11] offset:16
	global_load_dwordx4 v[236:239], v106, s[10:11]
	global_load_dwordx4 v[240:243], v106, s[4:5]
	global_load_dwordx4 v[244:247], v106, s[4:5] offset:16
	global_load_dwordx4 v[248:251], v106, s[10:11] offset:16
	v_mbcnt_hi_u32_b32 v68, -1, v234
	v_and_b32_e32 v73, 64, v68
	v_xor_b32_e32 v74, 1, v68
	v_add_u32_e32 v80, 64, v73
	v_cmp_lt_i32_e32 vcc, v74, v80
	s_mov_b32 s12, 0xf800000
	v_lshlrev_b32_e32 v72, 1, v72
	v_cndmask_b32_e32 v73, v68, v74, vcc
	v_lshlrev_b32_e32 v73, 2, v73
	v_lshlrev_b32_e32 v71, 1, v71
	v_lshlrev_b32_e32 v70, 1, v70
	s_waitcnt vmcnt(37)
	v_mul_f32_e32 v76, v3, v3
	v_fmac_f32_e32 v76, v2, v2
	v_fmac_f32_e32 v76, v4, v4
	v_fmac_f32_e32 v76, v5, v5
	s_waitcnt vmcnt(35)
	v_fmac_f32_e32 v76, v6, v6
	v_fmac_f32_e32 v76, v7, v7
	v_fmac_f32_e32 v76, v8, v8
	v_fmac_f32_e32 v76, v9, v9
	s_waitcnt vmcnt(34)
	v_fmac_f32_e32 v76, v14, v14
	v_fmac_f32_e32 v76, v15, v15
	v_fmac_f32_e32 v76, v16, v16
	v_fmac_f32_e32 v76, v17, v17
	s_waitcnt vmcnt(33)
	v_fmac_f32_e32 v76, v10, v10
	v_fmac_f32_e32 v76, v11, v11
	v_fmac_f32_e32 v76, v12, v12
	v_fmac_f32_e32 v76, v13, v13
	s_waitcnt vmcnt(32)
	v_fmac_f32_e32 v76, v22, v22
	v_fmac_f32_e32 v76, v23, v23
	v_fmac_f32_e32 v76, v24, v24
	v_fmac_f32_e32 v76, v25, v25
	s_waitcnt vmcnt(31)
	v_fmac_f32_e32 v76, v18, v18
	v_fmac_f32_e32 v76, v19, v19
	v_fmac_f32_e32 v76, v20, v20
	v_fmac_f32_e32 v76, v21, v21
	s_waitcnt vmcnt(30)
	v_fmac_f32_e32 v76, v30, v30
	v_fmac_f32_e32 v76, v31, v31
	v_fmac_f32_e32 v76, v32, v32
	v_fmac_f32_e32 v76, v33, v33
	s_waitcnt vmcnt(29)
	v_fmac_f32_e32 v76, v26, v26
	v_fmac_f32_e32 v76, v27, v27
	v_fmac_f32_e32 v76, v28, v28
	v_fmac_f32_e32 v76, v29, v29
	s_waitcnt vmcnt(28)
	v_fmac_f32_e32 v76, v42, v42
	v_fmac_f32_e32 v76, v43, v43
	v_fmac_f32_e32 v76, v44, v44
	v_fmac_f32_e32 v76, v45, v45
	s_waitcnt vmcnt(27)
	v_fmac_f32_e32 v76, v38, v38
	v_fmac_f32_e32 v76, v39, v39
	v_fmac_f32_e32 v76, v40, v40
	v_fmac_f32_e32 v76, v41, v41
	s_waitcnt vmcnt(26)
	v_fmac_f32_e32 v76, v62, v62
	v_fmac_f32_e32 v76, v63, v63
	v_fmac_f32_e32 v76, v64, v64
	v_fmac_f32_e32 v76, v65, v65
	s_waitcnt vmcnt(25)
	v_fmac_f32_e32 v76, v58, v58
	v_fmac_f32_e32 v76, v59, v59
	v_fmac_f32_e32 v76, v60, v60
	v_fmac_f32_e32 v76, v61, v61
	s_waitcnt vmcnt(24)
	v_fmac_f32_e32 v76, v54, v54
	v_fmac_f32_e32 v76, v55, v55
	v_fmac_f32_e32 v76, v56, v56
	v_fmac_f32_e32 v76, v57, v57
	s_waitcnt vmcnt(23)
	v_fmac_f32_e32 v76, v50, v50
	v_fmac_f32_e32 v76, v51, v51
	v_fmac_f32_e32 v76, v52, v52
	v_fmac_f32_e32 v76, v53, v53
	s_waitcnt vmcnt(22)
	v_fmac_f32_e32 v76, v46, v46
	v_fmac_f32_e32 v76, v47, v47
	v_fmac_f32_e32 v76, v48, v48
	v_fmac_f32_e32 v76, v49, v49
	v_fmac_f32_e32 v76, v34, v34
	v_pk_mul_f32 v[74:75], v[36:37], v[36:37]
	v_fmac_f32_e32 v76, v35, v35
	v_add_f32_e32 v74, v74, v76
	v_add_f32_e32 v74, v75, v74
	v_xor_b32_e32 v76, 2, v68
	v_cmp_lt_i32_e32 vcc, v76, v80
	s_waitcnt lgkmcnt(0)
	s_nop 1
	v_add_f32_dpp v74, v74, v74 quad_perm:[1,0,3,2] row_mask:0xf bank_mask:0xf
	v_cndmask_b32_e32 v76, v68, v76, vcc
	v_lshlrev_b32_e32 v78, 2, v76
	v_xor_b32_e32 v76, 4, v68
	v_cmp_lt_i32_e32 vcc, v76, v80
	s_waitcnt lgkmcnt(0)
	s_nop 1
	v_add_f32_dpp v74, v74, v74 quad_perm:[2,3,0,1] row_mask:0xf bank_mask:0xf
	v_cndmask_b32_e32 v76, v68, v76, vcc
	v_lshlrev_b32_e32 v77, 2, v76
	v_xor_b32_e32 v76, 8, v68
	v_cmp_lt_i32_e32 vcc, v76, v80
	s_waitcnt lgkmcnt(0)
	s_nop 1
	v_add_f32_dpp v74, v74, v74 row_half_mirror row_mask:0xf bank_mask:0xf
	v_cndmask_b32_e32 v76, v68, v76, vcc
	v_lshlrev_b32_e32 v76, 2, v76
	v_xor_b32_e32 v75, 16, v68
	v_cmp_lt_i32_e32 vcc, v75, v80
	s_waitcnt lgkmcnt(0)
	s_nop 1
	v_add_f32_dpp v81, v74, v74 row_mirror row_mask:0xf bank_mask:0xf
	v_cndmask_b32_e32 v75, v68, v75, vcc
	v_lshlrev_b32_e32 v75, 2, v75
	v_xor_b32_e32 v74, 32, v68
	v_cmp_lt_i32_e32 vcc, v74, v80
	s_nop 1
	v_cndmask_b32_e32 v68, v68, v74, vcc
	v_lshlrev_b32_e32 v74, 2, v68
	s_waitcnt lgkmcnt(0)
	v_mov_b32_e32 v68, v81
	v_mov_b32_e32 v98, v81
	s_nop 1
	v_permlane16_swap_b32_e32 v98, v68
	v_add_f32_e32 v68, v68, v98
	v_mov_b32_e32 v81, 0x358637bd
	s_waitcnt lgkmcnt(0)
	v_mov_b32_e32 v80, v68
	s_nop 1
	v_permlane32_swap_b32_e32 v80, v68
	v_add_f32_e32 v68, v68, v80
	v_fmamk_f32 v68, v68, 0x39800000, v81
	v_mul_f32_e32 v80, 0x4f800000, v68
	v_cmp_gt_f32_e32 vcc, s12, v68
	s_nop 1
	v_cndmask_b32_e32 v68, v68, v80, vcc
	v_sqrt_f32_e32 v98, v68
	v_mov_b32_e32 v80, 0x260
	v_add_u32_e32 v99, -1, v98
	v_add_u32_e32 v100, 1, v98
	v_fma_f32 v101, -v99, v98, v68
	v_fma_f32 v107, -v100, v98, v68
	v_cmp_ge_f32_e64 s[0:1], 0, v101
	s_nop 1
	v_cndmask_b32_e64 v98, v98, v99, s[0:1]
	v_cmp_lt_f32_e64 s[0:1], 0, v107
	v_or_b32_e32 v107, 0x800, v102
	s_nop 0
	v_cndmask_b32_e64 v98, v98, v100, s[0:1]
	v_mul_f32_e32 v99, 0x37800000, v98
	v_cndmask_b32_e32 v98, v98, v99, vcc
	v_cmp_class_f32_e32 vcc, v68, v80
	s_nop 1
	v_cndmask_b32_e32 v68, v98, v68, vcc
	v_div_scale_f32 v98, s[0:1], v68, v68, 1.0
	v_rcp_f32_e32 v99, v98
	v_div_scale_f32 v100, vcc, 1.0, v68, 1.0
	s_lshl_b64 s[0:1], s[6:7], 13
	v_fma_f32 v101, -v98, v99, 1.0
	v_fmac_f32_e32 v99, v101, v99
	v_mul_f32_e32 v101, v100, v99
	v_fma_f32 v108, -v98, v101, v100
	v_fmac_f32_e32 v101, v108, v99
	v_fma_f32 v98, -v98, v101, v100
	v_div_fmas_f32 v98, v98, v99, v101
	v_div_fixup_f32 v68, v98, v68, 1.0
	v_pk_mul_f32 v[2:3], v[2:3], v[68:69] op_sel_hi:[1,0]
	v_pk_mul_f32 v[4:5], v[4:5], v[68:69] op_sel_hi:[1,0]
	v_pk_mul_f32 v[98:99], v[6:7], v[68:69] op_sel_hi:[1,0]
	v_pk_mul_f32 v[100:101], v[8:9], v[68:69] op_sel_hi:[1,0]
	s_waitcnt vmcnt(18)
	v_pk_fma_f32 v[6:7], v[94:95], v[2:3], v[86:87]
	v_pk_fma_f32 v[8:9], v[96:97], v[4:5], v[88:89]
	v_pk_fma_f32 v[2:3], v[90:91], v[98:99], v[82:83]
	v_pk_fma_f32 v[4:5], v[92:93], v[100:101], v[84:85]
	global_store_dwordx4 v102, v[6:9], s[4:5]
	global_store_dwordx4 v102, v[2:5], s[4:5] offset:16
	global_load_dwordx4 v[82:85], v107, s[10:11]
	s_waitcnt vmcnt(20)
	v_mov_b64_e32 v[86:87], v[178:179]
	v_mov_b64_e32 v[88:89], v[180:181]
	s_waitcnt vmcnt(19)
	v_mov_b64_e32 v[90:91], v[182:183]
	v_mov_b64_e32 v[92:93], v[184:185]
	global_load_dwordx4 v[94:97], v107, s[10:11] offset:16
	v_pk_mul_f32 v[14:15], v[14:15], v[68:69] op_sel_hi:[1,0]
	v_pk_mul_f32 v[16:17], v[16:17], v[68:69] op_sel_hi:[1,0]
	v_pk_mul_f32 v[10:11], v[10:11], v[68:69] op_sel_hi:[1,0]
	v_pk_mul_f32 v[12:13], v[12:13], v[68:69] op_sel_hi:[1,0]
	v_pk_mul_f32 v[22:23], v[22:23], v[68:69] op_sel_hi:[1,0]
	v_pk_mul_f32 v[24:25], v[24:25], v[68:69] op_sel_hi:[1,0]
	v_pk_mul_f32 v[18:19], v[18:19], v[68:69] op_sel_hi:[1,0]
	v_pk_mul_f32 v[20:21], v[20:21], v[68:69] op_sel_hi:[1,0]
	v_pk_mul_f32 v[30:31], v[30:31], v[68:69] op_sel_hi:[1,0]
	v_pk_mul_f32 v[32:33], v[32:33], v[68:69] op_sel_hi:[1,0]
	v_pk_mul_f32 v[26:27], v[26:27], v[68:69] op_sel_hi:[1,0]
	v_pk_mul_f32 v[28:29], v[28:29], v[68:69] op_sel_hi:[1,0]
	v_pk_mul_f32 v[42:43], v[42:43], v[68:69] op_sel_hi:[1,0]
	v_pk_mul_f32 v[44:45], v[44:45], v[68:69] op_sel_hi:[1,0]
	v_pk_mul_f32 v[38:39], v[38:39], v[68:69] op_sel_hi:[1,0]
	v_pk_mul_f32 v[40:41], v[40:41], v[68:69] op_sel_hi:[1,0]
	v_pk_mul_f32 v[62:63], v[62:63], v[68:69] op_sel_hi:[1,0]
	v_pk_mul_f32 v[64:65], v[64:65], v[68:69] op_sel_hi:[1,0]
	v_pk_mul_f32 v[58:59], v[58:59], v[68:69] op_sel_hi:[1,0]
	v_pk_mul_f32 v[60:61], v[60:61], v[68:69] op_sel_hi:[1,0]
	v_pk_mul_f32 v[54:55], v[54:55], v[68:69] op_sel_hi:[1,0]
	v_pk_mul_f32 v[56:57], v[56:57], v[68:69] op_sel_hi:[1,0]
	v_pk_mul_f32 v[50:51], v[50:51], v[68:69] op_sel_hi:[1,0]
	v_pk_mul_f32 v[52:53], v[52:53], v[68:69] op_sel_hi:[1,0]
	v_pk_mul_f32 v[108:109], v[48:49], v[68:69] op_sel_hi:[1,0]
	v_pk_mul_f32 v[110:111], v[34:35], v[68:69] op_sel_hi:[1,0]
	v_pk_mul_f32 v[112:113], v[36:37], v[68:69] op_sel_hi:[1,0]
	v_pk_mul_f32 v[114:115], v[6:7], v[6:7]
	v_pk_mul_f32 v[116:117], v[8:9], v[8:9]
	v_pk_mul_f32 v[118:119], v[2:3], v[2:3]
	v_pk_mul_f32 v[120:121], v[4:5], v[4:5]
	s_add_u32 s0, s8, s0
	s_addc_u32 s1, s9, s1
	s_add_u32 s8, s0, 0x69900000
	s_addc_u32 s9, s1, 0
	s_waitcnt vmcnt(1)
	v_pk_fma_f32 v[14:15], v[82:83], v[14:15], v[86:87]
	v_pk_fma_f32 v[16:17], v[84:85], v[16:17], v[88:89]
	s_waitcnt vmcnt(0)
	v_pk_fma_f32 v[10:11], v[94:95], v[10:11], v[90:91]
	v_pk_fma_f32 v[12:13], v[96:97], v[12:13], v[92:93]
	global_store_dwordx4 v102, v[14:17], s[4:5] offset:2048
	global_store_dwordx4 v102, v[10:13], s[4:5] offset:2064
	s_nop 1
	v_mov_b64_e32 v[82:83], v[186:187]
	v_mov_b64_e32 v[84:85], v[188:189]
	v_mov_b64_e32 v[86:87], v[190:191]
	v_mov_b64_e32 v[88:89], v[192:193]
	v_mov_b64_e32 v[90:91], v[194:195]
	v_mov_b64_e32 v[92:93], v[196:197]
	v_mov_b64_e32 v[94:95], v[198:199]
	v_mov_b64_e32 v[96:97], v[200:201]
	v_pk_fma_f32 v[22:23], v[82:83], v[22:23], v[86:87]
	v_pk_fma_f32 v[24:25], v[84:85], v[24:25], v[88:89]
	v_pk_fma_f32 v[18:19], v[94:95], v[18:19], v[90:91]
	v_pk_fma_f32 v[20:21], v[96:97], v[20:21], v[92:93]
	global_store_dwordx4 v103, v[22:25], s[4:5]
	global_store_dwordx4 v103, v[18:21], s[4:5] offset:16
	s_nop 1
	v_mov_b64_e32 v[82:83], v[202:203]
	v_mov_b64_e32 v[84:85], v[204:205]
	v_mov_b64_e32 v[86:87], v[206:207]
	v_mov_b64_e32 v[88:89], v[208:209]
	v_mov_b64_e32 v[90:91], v[210:211]
	v_mov_b64_e32 v[92:93], v[212:213]
	v_mov_b64_e32 v[94:95], v[214:215]
	v_mov_b64_e32 v[96:97], v[216:217]
	v_pk_fma_f32 v[30:31], v[82:83], v[30:31], v[86:87]
	v_pk_fma_f32 v[32:33], v[84:85], v[32:33], v[88:89]
	v_pk_fma_f32 v[26:27], v[94:95], v[26:27], v[90:91]
	v_pk_fma_f32 v[28:29], v[96:97], v[28:29], v[92:93]
	global_store_dwordx4 v104, v[30:33], s[4:5]
	global_store_dwordx4 v104, v[26:29], s[4:5] offset:16
	s_nop 1
	v_mov_b64_e32 v[82:83], v[218:219]
	v_mov_b64_e32 v[84:85], v[220:221]
	v_mov_b64_e32 v[86:87], v[222:223]
	v_mov_b64_e32 v[88:89], v[224:225]
	v_mov_b64_e32 v[90:91], v[226:227]
	v_mov_b64_e32 v[92:93], v[228:229]
	v_mov_b64_e32 v[94:95], v[230:231]
	v_mov_b64_e32 v[96:97], v[232:233]
	v_pk_fma_f32 v[42:43], v[82:83], v[42:43], v[86:87]
	v_pk_fma_f32 v[44:45], v[84:85], v[44:45], v[88:89]
	v_pk_fma_f32 v[38:39], v[94:95], v[38:39], v[90:91]
	v_pk_fma_f32 v[40:41], v[96:97], v[40:41], v[92:93]
	global_store_dwordx4 v105, v[42:45], s[4:5]
	global_store_dwordx4 v105, v[38:41], s[4:5] offset:16
	s_nop 1
	v_mov_b64_e32 v[82:83], v[236:237]
	v_mov_b64_e32 v[84:85], v[238:239]
	v_mov_b64_e32 v[86:87], v[240:241]
	v_mov_b64_e32 v[88:89], v[242:243]
	v_mov_b64_e32 v[90:91], v[244:245]
	v_mov_b64_e32 v[92:93], v[246:247]
	v_mov_b64_e32 v[94:95], v[248:249]
	v_mov_b64_e32 v[96:97], v[250:251]
	v_pk_fma_f32 v[62:63], v[82:83], v[62:63], v[86:87]
	v_pk_fma_f32 v[64:65], v[84:85], v[64:65], v[88:89]
	v_pk_fma_f32 v[58:59], v[94:95], v[58:59], v[90:91]
	v_pk_fma_f32 v[60:61], v[96:97], v[60:61], v[92:93]
	global_store_dwordx4 v106, v[62:65], s[4:5]
	global_store_dwordx4 v106, v[58:61], s[4:5] offset:16
	global_load_dwordx4 v[82:85], v67, s[10:11]
	global_load_dwordx4 v[86:89], v67, s[4:5]
	global_load_dwordx4 v[90:93], v67, s[4:5] offset:16
	global_load_dwordx4 v[94:97], v67, s[10:11] offset:16
	global_load_dwordx4 v[98:101], v79, s[4:5] offset:16
	global_load_dwordx4 v[102:105], v79, s[4:5]
	v_pk_mul_f32 v[106:107], v[46:47], v[68:69] op_sel_hi:[1,0]
	s_waitcnt vmcnt(4)
	v_pk_fma_f32 v[46:47], v[82:83], v[54:55], v[86:87]
	v_pk_fma_f32 v[48:49], v[84:85], v[56:57], v[88:89]
	s_waitcnt vmcnt(2)
	v_pk_fma_f32 v[34:35], v[94:95], v[50:51], v[90:91]
	v_pk_fma_f32 v[36:37], v[96:97], v[52:53], v[92:93]
	global_store_dwordx4 v67, v[46:49], s[4:5]
	global_store_dwordx4 v67, v[34:37], s[4:5] offset:16
	global_load_dwordx4 v[50:53], v79, s[10:11] offset:16
	global_load_dwordx4 v[54:57], v79, s[10:11]
	v_add_f32_e32 v67, v114, v115
	v_add_f32_e32 v67, v116, v67
	v_add_f32_e32 v67, v117, v67
	v_add_f32_e32 v67, v118, v67
	v_add_f32_e32 v67, v119, v67
	v_add_f32_e32 v67, v120, v67
	v_add_f32_e32 v67, v121, v67
	v_pk_mul_f32 v[82:83], v[14:15], v[14:15]
	v_pk_mul_f32 v[84:85], v[16:17], v[16:17]
	v_add_f32_e32 v67, v82, v67
	v_add_f32_e32 v67, v83, v67
	v_add_f32_e32 v67, v84, v67
	v_pk_mul_f32 v[86:87], v[10:11], v[10:11]
	v_add_f32_e32 v67, v85, v67
	v_add_f32_e32 v67, v86, v67
	v_pk_mul_f32 v[88:89], v[12:13], v[12:13]
	v_add_f32_e32 v67, v87, v67
	v_add_f32_e32 v67, v88, v67
	v_add_f32_e32 v67, v89, v67
	v_pk_mul_f32 v[82:83], v[22:23], v[22:23]
	v_pk_mul_f32 v[84:85], v[24:25], v[24:25]
	v_add_f32_e32 v67, v82, v67
	v_add_f32_e32 v67, v83, v67
	v_add_f32_e32 v67, v84, v67
	v_pk_mul_f32 v[86:87], v[18:19], v[18:19]
	v_add_f32_e32 v67, v85, v67
	v_add_f32_e32 v67, v86, v67
	v_pk_mul_f32 v[88:89], v[20:21], v[20:21]
	v_add_f32_e32 v67, v87, v67
	v_add_f32_e32 v67, v88, v67
	v_add_f32_e32 v67, v89, v67
	v_pk_mul_f32 v[82:83], v[30:31], v[30:31]
	v_pk_mul_f32 v[84:85], v[32:33], v[32:33]
	v_add_f32_e32 v67, v82, v67
	v_add_f32_e32 v67, v83, v67
	v_add_f32_e32 v67, v84, v67
	v_pk_mul_f32 v[86:87], v[26:27], v[26:27]
	v_add_f32_e32 v67, v85, v67
	v_add_f32_e32 v67, v86, v67
	v_pk_mul_f32 v[88:89], v[28:29], v[28:29]
	v_add_f32_e32 v67, v87, v67
	v_add_f32_e32 v67, v88, v67
	v_add_f32_e32 v67, v89, v67
	v_pk_mul_f32 v[82:83], v[42:43], v[42:43]
	v_pk_mul_f32 v[84:85], v[44:45], v[44:45]
	v_add_f32_e32 v67, v82, v67
	v_add_f32_e32 v67, v83, v67
	v_add_f32_e32 v67, v84, v67
	v_pk_mul_f32 v[86:87], v[38:39], v[38:39]
	v_add_f32_e32 v67, v85, v67
	v_add_f32_e32 v67, v86, v67
	v_pk_mul_f32 v[88:89], v[40:41], v[40:41]
	v_add_f32_e32 v67, v87, v67
	v_add_f32_e32 v67, v88, v67
	v_add_f32_e32 v67, v89, v67
	v_pk_mul_f32 v[82:83], v[62:63], v[62:63]
	v_pk_mul_f32 v[84:85], v[64:65], v[64:65]
	v_add_f32_e32 v67, v82, v67
	v_add_f32_e32 v67, v83, v67
	v_add_f32_e32 v67, v84, v67
	v_pk_mul_f32 v[86:87], v[58:59], v[58:59]
	v_add_f32_e32 v67, v85, v67
	v_add_f32_e32 v67, v86, v67
	v_pk_mul_f32 v[88:89], v[60:61], v[60:61]
	v_add_f32_e32 v67, v87, v67
	v_add_f32_e32 v67, v88, v67
	v_add_f32_e32 v67, v89, v67
	v_pk_mul_f32 v[82:83], v[46:47], v[46:47]
	v_pk_mul_f32 v[84:85], v[48:49], v[48:49]
	v_add_f32_e32 v67, v82, v67
	v_add_f32_e32 v67, v83, v67
	v_add_f32_e32 v67, v84, v67
	v_pk_mul_f32 v[86:87], v[34:35], v[34:35]
	v_add_f32_e32 v67, v85, v67
	v_add_f32_e32 v67, v86, v67
	v_pk_mul_f32 v[88:89], v[36:37], v[36:37]
	v_add_f32_e32 v67, v87, v67
	v_add_f32_e32 v67, v88, v67
	v_add_f32_e32 v67, v89, v67
	s_waitcnt vmcnt(0)
	v_pk_fma_f32 v[54:55], v[54:55], v[106:107], v[102:103]
	v_pk_fma_f32 v[56:57], v[56:57], v[108:109], v[104:105]
	v_pk_mul_f32 v[82:83], v[54:55], v[54:55]
	v_pk_mul_f32 v[84:85], v[56:57], v[56:57]
	v_add_f32_e32 v67, v82, v67
	v_add_f32_e32 v67, v83, v67
	v_pk_fma_f32 v[50:51], v[50:51], v[110:111], v[98:99]
	v_add_f32_e32 v67, v84, v67
	v_pk_mul_f32 v[86:87], v[50:51], v[50:51]
	v_add_f32_e32 v67, v85, v67
	v_pk_fma_f32 v[52:53], v[52:53], v[112:113], v[100:101]
	v_add_f32_e32 v67, v86, v67
	v_pk_mul_f32 v[88:89], v[52:53], v[52:53]
	v_add_f32_e32 v67, v87, v67
	v_add_f32_e32 v67, v88, v67
	v_add_f32_e32 v67, v89, v67
	global_store_dwordx4 v79, v[54:57], s[4:5]
	global_store_dwordx4 v79, v[50:53], s[4:5] offset:16
	s_movk_i32 s10, 0x7fff
	s_waitcnt lgkmcnt(0)
	s_nop 1
	v_add_f32_dpp v67, v67, v67 quad_perm:[1,0,3,2] row_mask:0xf bank_mask:0xf
	s_waitcnt lgkmcnt(0)
	s_nop 1
	v_add_f32_dpp v67, v67, v67 quad_perm:[2,3,0,1] row_mask:0xf bank_mask:0xf
	s_waitcnt lgkmcnt(0)
	s_nop 1
	v_add_f32_dpp v67, v67, v67 row_half_mirror row_mask:0xf bank_mask:0xf
	s_waitcnt lgkmcnt(0)
	s_nop 1
	v_add_f32_dpp v68, v67, v67 row_mirror row_mask:0xf bank_mask:0xf
	v_mov_b32_e32 v67, 0
	s_waitcnt lgkmcnt(0)
	v_mov_b32_e32 v82, v68
	s_nop 1
	v_permlane16_swap_b32_e32 v82, v68
	v_add_f32_e32 v68, v68, v82
	s_waitcnt lgkmcnt(0)
	v_mov_b32_e32 v82, v68
	s_nop 1
	v_permlane32_swap_b32_e32 v82, v68
	v_add_f32_e32 v68, v68, v82
	v_fmac_f32_e32 v81, 0x39800000, v68
	v_mul_f32_e32 v68, 0x4f800000, v81
	v_cmp_gt_f32_e32 vcc, s12, v81
	s_nop 1
	v_cndmask_b32_e32 v68, v81, v68, vcc
	v_sqrt_f32_e32 v81, v68
	s_nop 0
	v_add_u32_e32 v82, -1, v81
	v_add_u32_e32 v83, 1, v81
	v_fma_f32 v84, -v82, v81, v68
	v_fma_f32 v85, -v83, v81, v68
	v_cmp_ge_f32_e64 s[0:1], 0, v84
	s_nop 1
	v_cndmask_b32_e64 v81, v81, v82, s[0:1]
	v_cmp_lt_f32_e64 s[0:1], 0, v85
	s_nop 1
	v_cndmask_b32_e64 v81, v81, v83, s[0:1]
	v_mul_f32_e32 v82, 0x37800000, v81
	v_cndmask_b32_e32 v81, v81, v82, vcc
	v_cmp_class_f32_e32 vcc, v68, v80
	s_nop 1
	v_cndmask_b32_e32 v68, v81, v68, vcc
	v_div_scale_f32 v80, s[0:1], v68, v68, 1.0
	v_rcp_f32_e32 v81, v80
	v_div_scale_f32 v79, vcc, 1.0, v68, 1.0
	v_fma_f32 v82, -v80, v81, 1.0
	v_fmac_f32_e32 v81, v82, v81
	v_mul_f32_e32 v82, v79, v81
	v_fma_f32 v83, -v80, v82, v79
	v_fmac_f32_e32 v82, v83, v81
	v_fma_f32 v79, -v80, v82, v79
	v_div_fmas_f32 v79, v79, v81, v82
	v_div_fixup_f32 v68, v79, v68, 1.0
	v_mul_f32_e32 v6, v6, v68
	v_mul_f32_e32 v7, v7, v68
	v_mul_f32_e32 v8, v8, v68
	v_mul_f32_e32 v9, v9, v68
	v_mul_f32_e32 v17, v17, v68
	v_mul_f32_e32 v21, v21, v68
	v_mul_f32_e32 v88, v26, v68
	v_mul_f32_e32 v89, v27, v68
	v_mul_f32_e32 v96, v38, v68
	v_mul_f32_e32 v97, v39, v68
	v_bfe_u32 v26, v6, 16, 1
	v_bfe_u32 v27, v7, 16, 1
	v_mul_f32_e32 v79, v2, v68
	v_mul_f32_e32 v80, v3, v68
	v_mul_f32_e32 v82, v5, v68
	v_mul_f32_e32 v25, v25, v68
	v_mul_f32_e32 v90, v28, v68
	v_mul_f32_e32 v91, v29, v68
	v_mul_f32_e32 v98, v40, v68
	v_mul_f32_e32 v99, v41, v68
	v_mul_f32_e32 v100, v62, v68
	v_mul_f32_e32 v101, v63, v68
	v_mul_f32_e32 v111, v49, v68
	v_mul_f32_e32 v115, v37, v68
	v_cvt_pk_bf16_f32 v2, v6, v7
	v_cvt_pk_bf16_f32 v3, v8, v9
	v_bfe_u32 v28, v8, 16, 1
	v_bfe_u32 v29, v9, 16, 1
	v_bfe_u32 v37, v17, 16, 1
	v_bfe_u32 v49, v21, 16, 1
	v_bfe_u32 v62, v96, 16, 1
	v_bfe_u32 v63, v97, 16, 1
	v_add3_u32 v6, v6, v26, s10
	v_add3_u32 v7, v7, v27, s10
	v_mul_f32_e32 v81, v4, v68
	v_mul_f32_e32 v14, v14, v68
	v_mul_f32_e32 v15, v15, v68
	v_mul_f32_e32 v16, v16, v68
	v_mul_f32_e32 v84, v30, v68
	v_mul_f32_e32 v85, v31, v68
	v_mul_f32_e32 v87, v33, v68
	v_mul_f32_e32 v92, v42, v68
	v_mul_f32_e32 v93, v43, v68
	v_mul_f32_e32 v95, v45, v68
	v_mul_f32_e32 v102, v64, v68
	v_mul_f32_e32 v103, v65, v68
	v_cvt_pk_bf16_f32 v4, v79, v80
	v_cvt_pk_bf16_f32 v5, v81, v82
	v_bfe_u32 v30, v79, 16, 1
	v_bfe_u32 v31, v80, 16, 1
	v_bfe_u32 v33, v82, 16, 1
	v_bfe_u32 v45, v25, 16, 1
	v_bfe_u32 v64, v98, 16, 1
	v_bfe_u32 v65, v99, 16, 1
	global_store_dwordx4 v130, v[2:5], s[8:9]
	v_add3_u32 v8, v8, v28, s10
	v_add3_u32 v9, v9, v29, s10
	v_cvt_pk_bf16_f32 v2, v14, v15
	v_cvt_pk_bf16_f32 v3, v16, v17
	v_add3_u32 v17, v17, v37, s10
	v_add3_u32 v37, v21, v49, s10
	v_add3_u32 v154, v96, v62, s10
	v_add3_u32 v155, v97, v63, s10
	v_and_b32_e32 v62, 0xffff0000, v6
	v_and_b32_e32 v63, 0xffff0000, v7
	v_mul_f32_e32 v86, v32, v68
	v_mul_f32_e32 v94, v44, v68
	v_mul_f32_e32 v104, v58, v68
	v_mul_f32_e32 v105, v59, v68
	v_bfe_u32 v32, v81, 16, 1
	v_bfe_u32 v58, v92, 16, 1
	v_bfe_u32 v59, v93, 16, 1
	v_add3_u32 v26, v79, v30, s10
	v_add3_u32 v27, v80, v31, s10
	v_add3_u32 v29, v82, v33, s10
	v_add3_u32 v33, v25, v45, s10
	v_add3_u32 v156, v98, v64, s10
	v_add3_u32 v157, v99, v65, s10
	v_and_b32_e32 v64, 0xffff0000, v8
	v_and_b32_e32 v65, 0xffff0000, v9
	v_and_b32_e32 v45, 0xffff0000, v37
	v_max3_f32 v37, |v62|, 0, |v63|
	v_mul_f32_e32 v106, v60, v68
	v_mul_f32_e32 v107, v61, v68
	v_mul_f32_e32 v112, v34, v68
	v_mul_f32_e32 v113, v35, v68
	v_bfe_u32 v34, v14, 16, 1
	v_bfe_u32 v35, v15, 16, 1
	v_bfe_u32 v60, v94, 16, 1
	v_bfe_u32 v61, v95, 16, 1
	v_add3_u32 v28, v81, v32, s10
	v_add3_u32 v150, v92, v58, s10
	v_add3_u32 v151, v93, v59, s10
	v_and_b32_e32 v58, 0xffff0000, v26
	v_and_b32_e32 v59, 0xffff0000, v27
	v_max3_f32 v37, v37, |v64|, |v65|
	v_mul_f32_e32 v10, v10, v68
	v_mul_f32_e32 v11, v11, v68
	v_mul_f32_e32 v114, v36, v68
	v_mul_f32_e32 v116, v54, v68
	v_mul_f32_e32 v117, v55, v68
	v_bfe_u32 v36, v16, 16, 1
	v_bfe_u32 v54, v88, 16, 1
	v_bfe_u32 v55, v89, 16, 1
	v_add3_u32 v14, v14, v34, s10
	v_add3_u32 v15, v15, v35, s10
	v_add3_u32 v152, v94, v60, s10
	v_add3_u32 v153, v95, v61, s10
	v_and_b32_e32 v60, 0xffff0000, v28
	v_and_b32_e32 v61, 0xffff0000, v29
	v_max3_f32 v37, v37, |v58|, |v59|
	v_mul_f32_e32 v12, v12, v68
	v_mul_f32_e32 v13, v13, v68
	v_mul_f32_e32 v118, v56, v68
	v_mul_f32_e32 v119, v57, v68
	v_bfe_u32 v38, v10, 16, 1
	v_bfe_u32 v39, v11, 16, 1
	v_bfe_u32 v56, v90, 16, 1
	v_bfe_u32 v57, v91, 16, 1
	v_add3_u32 v16, v16, v36, s10
	v_add3_u32 v79, v88, v54, s10
	v_add3_u32 v147, v89, v55, s10
	v_and_b32_e32 v54, 0xffff0000, v14
	v_and_b32_e32 v55, 0xffff0000, v15
	v_max3_f32 v37, v37, |v60|, |v61|
	v_mul_f32_e32 v22, v22, v68
	v_mul_f32_e32 v23, v23, v68
	v_mul_f32_e32 v120, v50, v68
	v_mul_f32_e32 v121, v51, v68
	v_bfe_u32 v40, v12, 16, 1
	v_bfe_u32 v41, v13, 16, 1
	v_bfe_u32 v50, v84, 16, 1
	v_bfe_u32 v51, v85, 16, 1
	v_cvt_pk_bf16_f32 v4, v10, v11
	v_add3_u32 v10, v10, v38, s10
	v_add3_u32 v11, v11, v39, s10
	v_add3_u32 v148, v90, v56, s10
	v_add3_u32 v149, v91, v57, s10
	v_and_b32_e32 v56, 0xffff0000, v16
	v_and_b32_e32 v57, 0xffff0000, v17
	v_max3_f32 v37, v37, |v54|, |v55|
	v_mul_f32_e32 v24, v24, v68
	v_mul_f32_e32 v18, v18, v68
	v_mul_f32_e32 v19, v19, v68
	v_mul_f32_e32 v20, v20, v68
	v_mul_f32_e32 v108, v46, v68
	v_mul_f32_e32 v109, v47, v68
	v_mul_f32_e32 v110, v48, v68
	v_mul_f32_e32 v122, v52, v68
	v_mul_f32_e32 v68, v53, v68
	v_bfe_u32 v42, v22, 16, 1
	v_bfe_u32 v43, v23, 16, 1
	v_bfe_u32 v52, v86, 16, 1
	v_bfe_u32 v53, v87, 16, 1
	v_cvt_pk_bf16_f32 v5, v12, v13
	v_add3_u32 v12, v12, v40, s10
	v_add3_u32 v13, v13, v41, s10
	v_add3_u32 v38, v84, v50, s10
	v_add3_u32 v39, v85, v51, s10
	v_and_b32_e32 v50, 0xffff0000, v10
	v_and_b32_e32 v51, 0xffff0000, v11
	v_max3_f32 v37, v37, |v56|, |v57|
	v_bfe_u32 v44, v24, 16, 1
	v_bfe_u32 v46, v18, 16, 1
	v_bfe_u32 v47, v19, 16, 1
	v_add3_u32 v30, v22, v42, s10
	v_add3_u32 v31, v23, v43, s10
	v_add3_u32 v40, v86, v52, s10
	v_add3_u32 v41, v87, v53, s10
	v_and_b32_e32 v52, 0xffff0000, v12
	v_and_b32_e32 v53, 0xffff0000, v13
	v_max3_f32 v37, v37, |v50|, |v51|
	v_bfe_u32 v48, v20, 16, 1
	v_add3_u32 v32, v24, v44, s10
	v_add3_u32 v34, v18, v46, s10
	v_add3_u32 v35, v19, v47, s10
	v_and_b32_e32 v46, 0xffff0000, v30
	v_and_b32_e32 v47, 0xffff0000, v31
	v_max3_f32 v37, v37, |v52|, |v53|
	v_add3_u32 v36, v20, v48, s10
	v_and_b32_e32 v48, 0xffff0000, v32
	v_and_b32_e32 v49, 0xffff0000, v33
	v_max3_f32 v37, v37, |v46|, |v47|
	v_and_b32_e32 v42, 0xffff0000, v34
	v_and_b32_e32 v43, 0xffff0000, v35
	v_max3_f32 v37, v37, |v48|, |v49|
	v_and_b32_e32 v44, 0xffff0000, v36
	v_max3_f32 v37, v37, |v42|, |v43|
	v_and_b32_e32 v38, 0xffff0000, v38
	v_and_b32_e32 v39, 0xffff0000, v39
	v_max3_f32 v37, v37, |v44|, |v45|
	v_and_b32_e32 v40, 0xffff0000, v40
	v_and_b32_e32 v41, 0xffff0000, v41
	v_max3_f32 v37, v37, |v38|, |v39|
	v_and_b32_e32 v33, 0xffff0000, v79
	v_and_b32_e32 v34, 0xffff0000, v147
	v_max3_f32 v37, v37, |v40|, |v41|
	v_and_b32_e32 v35, 0xffff0000, v148
	v_and_b32_e32 v36, 0xffff0000, v149
	v_max3_f32 v37, v37, |v33|, |v34|
	v_and_b32_e32 v29, 0xffff0000, v150
	v_and_b32_e32 v30, 0xffff0000, v151
	v_max3_f32 v37, v37, |v35|, |v36|
	v_and_b32_e32 v31, 0xffff0000, v152
	v_and_b32_e32 v32, 0xffff0000, v153
	v_max3_f32 v37, v37, |v29|, |v30|
	v_bfe_u32 v83, v100, 16, 1
	v_bfe_u32 v123, v101, 16, 1
	global_store_dwordx4 v130, v[2:5], s[8:9] offset:1024
	v_cvt_pk_bf16_f32 v80, v22, v23
	v_cvt_pk_bf16_f32 v81, v24, v25
	v_and_b32_e32 v25, 0xffff0000, v154
	v_and_b32_e32 v26, 0xffff0000, v155
	v_max3_f32 v37, v37, |v31|, |v32|
	v_bfe_u32 v124, v102, 16, 1
	v_bfe_u32 v125, v103, 16, 1
	v_add3_u32 v158, v100, v83, s10
	v_add3_u32 v123, v101, v123, s10
	v_and_b32_e32 v27, 0xffff0000, v156
	v_and_b32_e32 v28, 0xffff0000, v157
	v_max3_f32 v37, v37, |v25|, |v26|
	v_bfe_u32 v126, v104, 16, 1
	v_bfe_u32 v127, v105, 16, 1
	v_add3_u32 v124, v102, v124, s10
	v_add3_u32 v125, v103, v125, s10
	v_cvt_pk_bf16_f32 v82, v18, v19
	v_cvt_pk_bf16_f32 v83, v20, v21
	v_and_b32_e32 v21, 0xffff0000, v158
	v_and_b32_e32 v22, 0xffff0000, v123
	v_max3_f32 v37, v37, |v27|, |v28|
	v_bfe_u32 v128, v106, 16, 1
	v_bfe_u32 v129, v107, 16, 1
	v_add3_u32 v126, v104, v126, s10
	v_add3_u32 v127, v105, v127, s10
	v_and_b32_e32 v23, 0xffff0000, v124
	v_and_b32_e32 v24, 0xffff0000, v125
	v_max3_f32 v37, v37, |v21|, |v22|
	v_bfe_u32 v131, v108, 16, 1
	v_bfe_u32 v132, v109, 16, 1
	v_add3_u32 v128, v106, v128, s10
	v_add3_u32 v129, v107, v129, s10
	v_and_b32_e32 v17, 0xffff0000, v126
	v_and_b32_e32 v18, 0xffff0000, v127
	v_max3_f32 v37, v37, |v23|, |v24|
	v_bfe_u32 v133, v110, 16, 1
	v_bfe_u32 v134, v111, 16, 1
	v_add3_u32 v131, v108, v131, s10
	v_add3_u32 v132, v109, v132, s10
	v_and_b32_e32 v19, 0xffff0000, v128
	v_and_b32_e32 v20, 0xffff0000, v129
	v_max3_f32 v37, v37, |v17|, |v18|
	v_bfe_u32 v135, v112, 16, 1
	v_bfe_u32 v136, v113, 16, 1
	v_add3_u32 v133, v110, v133, s10
	v_add3_u32 v134, v111, v134, s10
	v_and_b32_e32 v13, 0xffff0000, v131
	v_and_b32_e32 v14, 0xffff0000, v132
	v_max3_f32 v37, v37, |v19|, |v20|
	v_bfe_u32 v137, v114, 16, 1
	v_bfe_u32 v138, v115, 16, 1
	v_add3_u32 v135, v112, v135, s10
	v_add3_u32 v136, v113, v136, s10
	v_and_b32_e32 v15, 0xffff0000, v133
	v_and_b32_e32 v16, 0xffff0000, v134
	v_max3_f32 v37, v37, |v13|, |v14|
	v_bfe_u32 v139, v116, 16, 1
	v_bfe_u32 v140, v117, 16, 1
	v_add3_u32 v137, v114, v137, s10
	v_add3_u32 v138, v115, v138, s10
	v_and_b32_e32 v9, 0xffff0000, v135
	v_and_b32_e32 v10, 0xffff0000, v136
	v_max3_f32 v37, v37, |v15|, |v16|
	v_bfe_u32 v141, v118, 16, 1
	v_bfe_u32 v142, v119, 16, 1
	v_add3_u32 v139, v116, v139, s10
	v_add3_u32 v140, v117, v140, s10
	v_and_b32_e32 v11, 0xffff0000, v137
	v_and_b32_e32 v12, 0xffff0000, v138
	v_max3_f32 v37, v37, |v9|, |v10|
	v_bfe_u32 v143, v120, 16, 1
	v_bfe_u32 v144, v121, 16, 1
	v_add3_u32 v141, v118, v141, s10
	v_add3_u32 v142, v119, v142, s10
	v_and_b32_e32 v5, 0xffff0000, v139
	v_and_b32_e32 v6, 0xffff0000, v140
	v_max3_f32 v37, v37, |v11|, |v12|
	v_bfe_u32 v145, v122, 16, 1
	v_bfe_u32 v146, v68, 16, 1
	v_add3_u32 v143, v120, v143, s10
	v_add3_u32 v144, v121, v144, s10
	v_and_b32_e32 v7, 0xffff0000, v141
	v_and_b32_e32 v8, 0xffff0000, v142
	v_max3_f32 v37, v37, |v5|, |v6|
	v_add3_u32 v145, v122, v145, s10
	v_add3_u32 v146, v68, v146, s10
	v_and_b32_e32 v2, 0xffff0000, v143
	v_and_b32_e32 v3, 0xffff0000, v144
	v_max3_f32 v37, v37, |v7|, |v8|
	v_and_b32_e32 v4, 0xffff0000, v145
	v_max3_f32 v79, v37, |v2|, |v3|
	v_and_b32_e32 v37, 0xffff0000, v146
	v_max3_f32 v79, v79, |v4|, |v37|
	ds_bpermute_b32 v73, v73, v79
	global_store_dwordx4 v130, v[80:83], s[8:9] offset:2048
	v_cmp_eq_u32_e32 vcc, 0, v1
	s_waitcnt lgkmcnt(0)
	v_max_f32_e32 v73, v73, v73
	v_max_f32_e32 v73, v79, v73
	v_cvt_pk_bf16_f32 v80, v84, v85
	ds_bpermute_b32 v84, v78, v73
	v_cvt_pk_bf16_f32 v81, v86, v87
	v_cvt_pk_bf16_f32 v82, v88, v89
	v_cvt_pk_bf16_f32 v83, v90, v91
	global_store_dwordx4 v130, v[80:83], s[8:9] offset:3072
	s_nop 1
	v_cvt_pk_bf16_f32 v80, v92, v93
	v_cvt_pk_bf16_f32 v81, v94, v95
	v_cvt_pk_bf16_f32 v82, v96, v97
	v_cvt_pk_bf16_f32 v83, v98, v99
	global_store_dwordx4 v72, v[80:83], s[8:9]
	s_waitcnt lgkmcnt(0)
	v_max_f32_e32 v72, v84, v84
	v_max_f32_e32 v72, v73, v72
	ds_bpermute_b32 v73, v77, v72
	v_cvt_pk_bf16_f32 v78, v100, v101
	v_cvt_pk_bf16_f32 v79, v102, v103
	v_cvt_pk_bf16_f32 v80, v104, v105
	v_cvt_pk_bf16_f32 v81, v106, v107
	global_store_dwordx4 v71, v[78:81], s[8:9]
	s_waitcnt lgkmcnt(0)
	v_max_f32_e32 v71, v73, v73
	v_max_f32_e32 v71, v72, v71
	ds_bpermute_b32 v72, v76, v71
	v_cvt_pk_bf16_f32 v78, v108, v109
	v_cvt_pk_bf16_f32 v79, v110, v111
	v_cvt_pk_bf16_f32 v80, v112, v113
	v_cvt_pk_bf16_f32 v81, v114, v115
	s_waitcnt lgkmcnt(0)
	v_max_f32_e32 v72, v72, v72
	v_max_f32_e32 v73, v71, v72
	ds_bpermute_b32 v75, v75, v73
	global_store_dwordx4 v70, v[78:81], s[8:9]
	v_cvt_pk_bf16_f32 v70, v116, v117
	v_cvt_pk_bf16_f32 v71, v118, v119
	v_cvt_pk_bf16_f32 v72, v120, v121
	s_waitcnt lgkmcnt(0)
	v_max_f32_e32 v75, v75, v75
	v_max_f32_e32 v75, v73, v75
	ds_bpermute_b32 v74, v74, v75
	v_cvt_pk_bf16_f32 v73, v122, v68
	v_lshlrev_b32_e32 v68, 1, v69
	global_store_dwordx4 v68, v[70:73], s[8:9]
	s_waitcnt lgkmcnt(0)
	v_max_f32_e32 v1, v74, v74
	v_max_f32_e32 v1, v75, v1
	s_and_saveexec_b64 s[0:1], vcc
	s_cbranch_execz .LBB0_1635
	s_lshl_b64 s[4:5], s[6:7], 2
	s_add_u32 s4, s56, s4
	v_mul_f32_e32 v68, 0x3c010204, v1
	s_addc_u32 s5, s57, s5
	global_store_dword v67, v68, s[4:5]

.LBB0_2029:
	s_cmp_lt_i32 s8, 32
	s_cbranch_scc0 .LBB0_2031
	s_ashr_i32 s9, s8, 31
	s_lshl_b64 s[0:1], s[8:9], 14
	s_waitcnt lgkmcnt(0)
	s_add_u32 s8, s6, s0
	s_addc_u32 s9, s7, s1
	s_add_u32 s6, s8, 0x69ac0000
	s_addc_u32 s7, s9, 0
	global_load_dwordx4 v[28:31], v64, s[6:7]
	v_or_b32_e32 v65, 0x3800, v64
	global_load_dwordx4 v[0:3], v65, s[6:7] offset:16
	global_load_dwordx4 v[60:63], v64, s[6:7] offset:16
	global_load_dwordx4 v[56:59], v64, s[6:7] offset:2048
	global_load_dwordx4 v[52:55], v64, s[6:7] offset:2064
	v_or_b32_e32 v86, 0x1000, v64
	global_load_dwordx4 v[48:51], v86, s[6:7]
	global_load_dwordx4 v[44:47], v86, s[6:7] offset:16
	v_or_b32_e32 v87, 0x1800, v64
	global_load_dwordx4 v[40:43], v87, s[6:7]
	global_load_dwordx4 v[36:39], v87, s[6:7] offset:16
	v_or_b32_e32 v88, 0x2000, v64
	global_load_dwordx4 v[32:35], v88, s[6:7]
	global_load_dwordx4 v[24:27], v88, s[6:7] offset:16
	v_or_b32_e32 v89, 0x2800, v64
	global_load_dwordx4 v[20:23], v89, s[6:7]
	global_load_dwordx4 v[16:19], v89, s[6:7] offset:16
	global_load_dwordx4 v[96:99], v65, s[6:7]
	v_or_b32_e32 v67, 0x3000, v64
	global_load_dwordx4 v[12:15], v67, s[6:7]
	global_load_dwordx4 v[8:11], v67, s[6:7] offset:16
	s_waitcnt vmcnt(2)
	v_mov_b64_e32 v[4:5], v[96:97]
	v_mov_b64_e32 v[6:7], v[98:99]
	v_mbcnt_hi_u32_b32 v66, -1, v234
	v_and_b32_e32 v68, 64, v66
	s_add_u32 s6, s8, 0x69b40000
	v_xor_b32_e32 v69, 1, v66
	v_add_u32_e32 v90, 64, v68
	s_addc_u32 s7, s9, 0
	v_cmp_lt_i32_e32 vcc, v69, v90
	s_add_u32 s2, s2, 0x4000
	s_addc_u32 s3, s3, 0
	v_cndmask_b32_e32 v68, v66, v69, vcc
	v_lshlrev_b32_e32 v91, 2, v68
	global_load_dwordx4 v[68:71], v64, s[6:7] offset:16
	global_load_dwordx4 v[72:75], v64, s[6:7]
	global_load_dwordx4 v[76:79], v64, s[2:3] offset:16
	global_load_dwordx4 v[80:83], v64, s[2:3]
	s_mov_b32 s8, 0xf800000
	s_add_u32 s0, s4, s0
	s_addc_u32 s5, s5, s1
	s_add_u32 s4, s0, 0x8000000
	s_addc_u32 s5, s5, 0
	v_pk_mul_f32 v[84:85], v[2:3], v[2:3]
	v_mul_f32_e32 v92, v29, v29
	v_fmac_f32_e32 v92, v28, v28
	v_fmac_f32_e32 v92, v30, v30
	v_fmac_f32_e32 v92, v31, v31
	v_fmac_f32_e32 v92, v60, v60
	v_fmac_f32_e32 v92, v61, v61
	v_fmac_f32_e32 v92, v62, v62
	v_fmac_f32_e32 v92, v63, v63
	v_fmac_f32_e32 v92, v56, v56
	v_fmac_f32_e32 v92, v57, v57
	v_fmac_f32_e32 v92, v58, v58
	v_fmac_f32_e32 v92, v59, v59
	v_fmac_f32_e32 v92, v52, v52
	v_fmac_f32_e32 v92, v53, v53
	v_fmac_f32_e32 v92, v54, v54
	v_fmac_f32_e32 v92, v55, v55
	v_fmac_f32_e32 v92, v48, v48
	v_fmac_f32_e32 v92, v49, v49
	v_fmac_f32_e32 v92, v50, v50
	v_fmac_f32_e32 v92, v51, v51
	v_fmac_f32_e32 v92, v44, v44
	v_fmac_f32_e32 v92, v45, v45
	v_fmac_f32_e32 v92, v46, v46
	v_fmac_f32_e32 v92, v47, v47
	v_fmac_f32_e32 v92, v40, v40
	v_fmac_f32_e32 v92, v41, v41
	v_fmac_f32_e32 v92, v42, v42
	v_fmac_f32_e32 v92, v43, v43
	v_fmac_f32_e32 v92, v36, v36
	v_fmac_f32_e32 v92, v37, v37
	v_fmac_f32_e32 v92, v38, v38
	v_fmac_f32_e32 v92, v39, v39
	v_fmac_f32_e32 v92, v32, v32
	v_fmac_f32_e32 v92, v33, v33
	v_fmac_f32_e32 v92, v34, v34
	v_fmac_f32_e32 v92, v35, v35
	v_fmac_f32_e32 v92, v24, v24
	v_fmac_f32_e32 v92, v25, v25
	v_fmac_f32_e32 v92, v26, v26
	v_fmac_f32_e32 v92, v27, v27
	v_fmac_f32_e32 v92, v20, v20
	v_fmac_f32_e32 v92, v21, v21
	v_fmac_f32_e32 v92, v22, v22
	v_fmac_f32_e32 v92, v23, v23
	v_fmac_f32_e32 v92, v16, v16
	v_fmac_f32_e32 v92, v17, v17
	v_fmac_f32_e32 v92, v18, v18
	v_fmac_f32_e32 v92, v19, v19
	s_waitcnt vmcnt(5)
	v_fmac_f32_e32 v92, v12, v12
	v_fmac_f32_e32 v92, v13, v13
	v_fmac_f32_e32 v92, v14, v14
	v_fmac_f32_e32 v92, v15, v15
	s_waitcnt vmcnt(4)
	v_fmac_f32_e32 v92, v8, v8
	v_fmac_f32_e32 v92, v9, v9
	v_fmac_f32_e32 v92, v10, v10
	v_fmac_f32_e32 v92, v11, v11
	v_fmac_f32_e32 v92, v4, v4
	v_fmac_f32_e32 v92, v5, v5
	v_fmac_f32_e32 v92, v6, v6
	v_fmac_f32_e32 v92, v7, v7
	v_fmac_f32_e32 v92, v0, v0
	v_fmac_f32_e32 v92, v1, v1
	v_add_f32_e32 v84, v84, v92
	v_add_f32_e32 v84, v85, v84
	v_xor_b32_e32 v91, 2, v66
	v_cmp_lt_i32_e32 vcc, v91, v90
	s_waitcnt lgkmcnt(0)
	s_nop 1
	v_add_f32_dpp v84, v84, v84 quad_perm:[1,0,3,2] row_mask:0xf bank_mask:0xf
	v_cndmask_b32_e32 v91, v66, v91, vcc
	v_lshlrev_b32_e32 v91, 2, v91
	v_xor_b32_e32 v91, 4, v66
	v_cmp_lt_i32_e32 vcc, v91, v90
	s_waitcnt lgkmcnt(0)
	s_nop 1
	v_add_f32_dpp v84, v84, v84 quad_perm:[2,3,0,1] row_mask:0xf bank_mask:0xf
	v_cndmask_b32_e32 v91, v66, v91, vcc
	v_lshlrev_b32_e32 v91, 2, v91
	v_xor_b32_e32 v91, 8, v66
	v_cmp_lt_i32_e32 vcc, v91, v90
	s_waitcnt lgkmcnt(0)
	s_nop 1
	v_add_f32_dpp v84, v84, v84 row_half_mirror row_mask:0xf bank_mask:0xf
	v_cndmask_b32_e32 v91, v66, v91, vcc
	v_lshlrev_b32_e32 v91, 2, v91
	v_xor_b32_e32 v91, 16, v66
	v_cmp_lt_i32_e32 vcc, v91, v90
	s_waitcnt lgkmcnt(0)
	s_nop 1
	v_add_f32_dpp v84, v84, v84 row_mirror row_mask:0xf bank_mask:0xf
	v_cndmask_b32_e32 v91, v66, v91, vcc
	v_lshlrev_b32_e32 v91, 2, v91
	v_xor_b32_e32 v91, 32, v66
	v_cmp_lt_i32_e32 vcc, v91, v90
	v_mov_b32_e32 v90, 0x260
	s_waitcnt lgkmcnt(0)
	v_mov_b32_e32 v85, v84
	s_nop 1
	v_permlane16_swap_b32_e32 v85, v84
	v_add_f32_e32 v84, v84, v85
	v_cndmask_b32_e32 v66, v66, v91, vcc
	v_lshlrev_b32_e32 v66, 2, v66
	ds_bpermute_b32 v66, v66, v84
	v_mov_b32_e32 v85, 0x358637bd
	v_or_b32_e32 v91, 0x800, v64
	s_waitcnt lgkmcnt(0)
	v_add_f32_e32 v66, v84, v66
	v_fmac_f32_e32 v85, 0x39800000, v66
	v_mul_f32_e32 v66, 0x4f800000, v85
	v_cmp_gt_f32_e32 vcc, s8, v85
	s_nop 1
	v_cndmask_b32_e32 v66, v85, v66, vcc
	v_sqrt_f32_e32 v84, v66
	s_nop 0
	v_add_u32_e32 v85, -1, v84
	v_add_u32_e32 v92, 1, v84
	v_fma_f32 v93, -v85, v84, v66
	v_fma_f32 v94, -v92, v84, v66
	v_cmp_ge_f32_e64 s[0:1], 0, v93
	s_nop 1
	v_cndmask_b32_e64 v84, v84, v85, s[0:1]
	v_cmp_lt_f32_e64 s[0:1], 0, v94
	s_nop 1
	v_cndmask_b32_e64 v84, v84, v92, s[0:1]
	v_mul_f32_e32 v85, 0x37800000, v84
	v_cndmask_b32_e32 v84, v84, v85, vcc
	v_cmp_class_f32_e32 vcc, v66, v90
	s_nop 1
	v_cndmask_b32_e32 v66, v84, v66, vcc
	v_div_scale_f32 v84, s[0:1], v66, v66, 1.0
	v_rcp_f32_e32 v85, v84
	v_div_scale_f32 v90, vcc, 1.0, v66, 1.0
	v_fma_f32 v92, -v84, v85, 1.0
	v_fmac_f32_e32 v85, v92, v85
	v_mul_f32_e32 v92, v90, v85
	v_fma_f32 v93, -v84, v92, v90
	v_fmac_f32_e32 v92, v93, v85
	v_fma_f32 v84, -v84, v92, v90
	v_div_fmas_f32 v84, v84, v85, v92
	v_div_fixup_f32 v66, v84, v66, 1.0
	v_pk_mul_f32 v[28:29], v[28:29], v[66:67] op_sel_hi:[1,0]
	v_pk_mul_f32 v[30:31], v[30:31], v[66:67] op_sel_hi:[1,0]
	v_pk_mul_f32 v[60:61], v[60:61], v[66:67] op_sel_hi:[1,0]
	v_pk_mul_f32 v[62:63], v[62:63], v[66:67] op_sel_hi:[1,0]
	s_waitcnt vmcnt(0)
	v_pk_fma_f32 v[30:31], v[82:83], v[30:31], v[74:75]
	v_pk_fma_f32 v[28:29], v[80:81], v[28:29], v[72:73]
	v_pk_fma_f32 v[62:63], v[78:79], v[62:63], v[70:71]
	v_pk_fma_f32 v[60:61], v[76:77], v[60:61], v[68:69]
	global_store_dwordx4 v64, v[28:31], s[4:5]
	global_store_dwordx4 v64, v[60:63], s[4:5] offset:16
	global_load_dwordx4 v[28:31], v91, s[2:3]
	s_nop 0
	global_load_dwordx4 v[60:63], v64, s[6:7] offset:2048
	global_load_dwordx4 v[68:71], v64, s[6:7] offset:2064
	global_load_dwordx4 v[72:75], v91, s[2:3] offset:16
	v_pk_mul_f32 v[58:59], v[58:59], v[66:67] op_sel_hi:[1,0]
	v_pk_mul_f32 v[56:57], v[56:57], v[66:67] op_sel_hi:[1,0]
	v_pk_mul_f32 v[54:55], v[54:55], v[66:67] op_sel_hi:[1,0]
	v_pk_mul_f32 v[52:53], v[52:53], v[66:67] op_sel_hi:[1,0]
	v_pk_mul_f32 v[50:51], v[50:51], v[66:67] op_sel_hi:[1,0]
	v_pk_mul_f32 v[48:49], v[48:49], v[66:67] op_sel_hi:[1,0]
	v_pk_mul_f32 v[46:47], v[46:47], v[66:67] op_sel_hi:[1,0]
	v_pk_mul_f32 v[44:45], v[44:45], v[66:67] op_sel_hi:[1,0]
	v_pk_mul_f32 v[42:43], v[42:43], v[66:67] op_sel_hi:[1,0]
	v_pk_mul_f32 v[40:41], v[40:41], v[66:67] op_sel_hi:[1,0]
	v_pk_mul_f32 v[38:39], v[38:39], v[66:67] op_sel_hi:[1,0]
	v_pk_mul_f32 v[36:37], v[36:37], v[66:67] op_sel_hi:[1,0]
	v_pk_mul_f32 v[34:35], v[34:35], v[66:67] op_sel_hi:[1,0]
	v_pk_mul_f32 v[32:33], v[32:33], v[66:67] op_sel_hi:[1,0]
	v_pk_mul_f32 v[22:23], v[22:23], v[66:67] op_sel_hi:[1,0]
	v_pk_mul_f32 v[20:21], v[20:21], v[66:67] op_sel_hi:[1,0]
	v_pk_mul_f32 v[14:15], v[14:15], v[66:67] op_sel_hi:[1,0]
	v_pk_mul_f32 v[12:13], v[12:13], v[66:67] op_sel_hi:[1,0]
	v_pk_mul_f32 v[6:7], v[6:7], v[66:67] op_sel_hi:[1,0]
	v_pk_mul_f32 v[4:5], v[4:5], v[66:67] op_sel_hi:[1,0]
	s_waitcnt vmcnt(2)
	v_pk_fma_f32 v[28:29], v[28:29], v[56:57], v[60:61]
	v_pk_fma_f32 v[30:31], v[30:31], v[58:59], v[62:63]
	s_waitcnt vmcnt(0)
	v_pk_fma_f32 v[52:53], v[72:73], v[52:53], v[68:69]
	v_pk_fma_f32 v[54:55], v[74:75], v[54:55], v[70:71]
	global_store_dwordx4 v64, v[28:31], s[4:5] offset:2048
	global_store_dwordx4 v64, v[52:55], s[4:5] offset:2064
	global_load_dwordx4 v[28:31], v86, s[2:3]
	s_nop 0
	global_load_dwordx4 v[52:55], v86, s[6:7]
	global_load_dwordx4 v[56:59], v86, s[6:7] offset:16
	global_load_dwordx4 v[60:63], v86, s[2:3] offset:16
	s_waitcnt vmcnt(2)
	v_pk_fma_f32 v[28:29], v[28:29], v[48:49], v[52:53]
	v_pk_fma_f32 v[30:31], v[30:31], v[50:51], v[54:55]
	s_waitcnt vmcnt(0)
	v_pk_fma_f32 v[44:45], v[60:61], v[44:45], v[56:57]
	v_pk_fma_f32 v[46:47], v[62:63], v[46:47], v[58:59]
	global_store_dwordx4 v86, v[28:31], s[4:5]
	global_store_dwordx4 v86, v[44:47], s[4:5] offset:16
	global_load_dwordx4 v[28:31], v87, s[2:3]
	s_nop 0
	global_load_dwordx4 v[44:47], v87, s[6:7]
	global_load_dwordx4 v[48:51], v87, s[6:7] offset:16
	global_load_dwordx4 v[52:55], v87, s[2:3] offset:16
	s_waitcnt vmcnt(2)
	v_pk_fma_f32 v[28:29], v[28:29], v[40:41], v[44:45]
	v_pk_fma_f32 v[30:31], v[30:31], v[42:43], v[46:47]
	s_waitcnt vmcnt(0)
	v_pk_fma_f32 v[36:37], v[52:53], v[36:37], v[48:49]
	v_pk_fma_f32 v[38:39], v[54:55], v[38:39], v[50:51]
	global_store_dwordx4 v87, v[28:31], s[4:5]
	global_store_dwordx4 v87, v[36:39], s[4:5] offset:16
	global_load_dwordx4 v[28:31], v88, s[2:3]
	s_nop 0
	global_load_dwordx4 v[36:39], v88, s[6:7]
	global_load_dwordx4 v[40:43], v88, s[6:7] offset:16
	global_load_dwordx4 v[44:47], v88, s[2:3] offset:16
	v_pk_mul_f32 v[48:49], v[26:27], v[66:67] op_sel_hi:[1,0]
	v_pk_mul_f32 v[50:51], v[24:25], v[66:67] op_sel_hi:[1,0]
	s_waitcnt vmcnt(2)
	v_pk_fma_f32 v[24:25], v[28:29], v[32:33], v[36:37]
	v_pk_fma_f32 v[26:27], v[30:31], v[34:35], v[38:39]
	s_waitcnt vmcnt(0)
	v_pk_fma_f32 v[28:29], v[44:45], v[50:51], v[40:41]
	v_pk_fma_f32 v[30:31], v[46:47], v[48:49], v[42:43]
	global_store_dwordx4 v88, v[24:27], s[4:5]
	global_store_dwordx4 v88, v[28:31], s[4:5] offset:16
	global_load_dwordx4 v[24:27], v89, s[2:3]
	s_nop 0
	global_load_dwordx4 v[28:31], v89, s[6:7]
	global_load_dwordx4 v[32:35], v89, s[6:7] offset:16
	global_load_dwordx4 v[36:39], v89, s[2:3] offset:16
	v_pk_mul_f32 v[40:41], v[18:19], v[66:67] op_sel_hi:[1,0]
	v_pk_mul_f32 v[42:43], v[16:17], v[66:67] op_sel_hi:[1,0]
	s_waitcnt vmcnt(2)
	v_pk_fma_f32 v[16:17], v[24:25], v[20:21], v[28:29]
	v_pk_fma_f32 v[18:19], v[26:27], v[22:23], v[30:31]
	s_waitcnt vmcnt(0)
	v_pk_fma_f32 v[20:21], v[36:37], v[42:43], v[32:33]
	v_pk_fma_f32 v[22:23], v[38:39], v[40:41], v[34:35]
	global_store_dwordx4 v89, v[16:19], s[4:5]
	global_store_dwordx4 v89, v[20:23], s[4:5] offset:16
	global_load_dwordx4 v[16:19], v67, s[2:3]
	s_nop 0
	global_load_dwordx4 v[20:23], v67, s[6:7]
	global_load_dwordx4 v[24:27], v67, s[6:7] offset:16
	global_load_dwordx4 v[28:31], v67, s[2:3] offset:16
	v_pk_mul_f32 v[32:33], v[10:11], v[66:67] op_sel_hi:[1,0]
	v_pk_mul_f32 v[34:35], v[8:9], v[66:67] op_sel_hi:[1,0]
	s_waitcnt vmcnt(2)
	v_pk_fma_f32 v[8:9], v[16:17], v[12:13], v[20:21]
	v_pk_fma_f32 v[10:11], v[18:19], v[14:15], v[22:23]
	s_waitcnt vmcnt(0)
	v_pk_fma_f32 v[12:13], v[28:29], v[34:35], v[24:25]
	v_pk_fma_f32 v[14:15], v[30:31], v[32:33], v[26:27]
	global_store_dwordx4 v67, v[8:11], s[4:5]
	global_store_dwordx4 v67, v[12:15], s[4:5] offset:16
	global_load_dwordx4 v[8:11], v65, s[2:3]
	s_nop 0
	global_load_dwordx4 v[12:15], v65, s[6:7]
	global_load_dwordx4 v[16:19], v65, s[6:7] offset:16
	global_load_dwordx4 v[20:23], v65, s[2:3] offset:16
	v_pk_mul_f32 v[24:25], v[2:3], v[66:67] op_sel_hi:[1,0]
	v_pk_mul_f32 v[26:27], v[0:1], v[66:67] op_sel_hi:[1,0]
	s_waitcnt vmcnt(2)
	v_pk_fma_f32 v[0:1], v[8:9], v[4:5], v[12:13]
	v_pk_fma_f32 v[2:3], v[10:11], v[6:7], v[14:15]
	s_waitcnt vmcnt(0)
	v_pk_fma_f32 v[4:5], v[20:21], v[26:27], v[16:17]
	v_pk_fma_f32 v[6:7], v[22:23], v[24:25], v[18:19]
	global_store_dwordx4 v65, v[0:3], s[4:5]
	global_store_dwordx4 v65, v[4:7], s[4:5] offset:16
